# GEMM main loops: first 4 MFMAs of each MFMA phase issued before the opening barrier (fill the partner's MFMA-phase gaps; barrier count unchanged)
# baseline (speedup 1.0000x reference)
; #define PG8_STAGE(bufoff, gbase, voff) do { _Pragma("unroll") for (int _i = 0; _i < 2; ++_i) \
;         __builtin_amdgcn_global_load_lds((const unsigned*)((const char*)(gbase) + (voff)[_i]), (LAS unsigned*)(lds + (bufoff) + ldsw + _i * 8192), 16, 0, 0); } while (0)
; #define PG8_LDA(dst, b, h) do { _Pragma("unroll") for (int m = 0; m < 4; ++m) _Pragma("unroll") for (int k = 0; k < 2; ++k) dst[m][k] = *(const LAS bf16x8*)(lds + PG8_SA(b, h) + aoff + m * 2048 + k * 1024); } while (0)
; #define PG8_LDB(dst, b, h) do { _Pragma("unroll") for (int n = 0; n < 2; ++n) _Pragma("unroll") for (int k = 0; k < 2; ++k) dst[n][k] = *(const LAS bf16x8*)(lds + PG8_SB(b, h) + boff + n * 2048 + k * 1024); } while (0)
; #define PG8_MMA(ai, bj, At, Bt) do { __builtin_amdgcn_s_setprio(1); _Pragma("unroll") for (int m = 0; m < 4; ++m) _Pragma("unroll") for (int n = 0; n < 2; ++n) _Pragma("unroll") for (int k = 0; k < 2; ++k) \
;         acc[ai][bj][m][n] = __builtin_amdgcn_mfma_f32_16x16x32_bf16(Bt[n][k], At[m][k], acc[ai][bj][m][n], 0, 0, 0); __builtin_amdgcn_s_setprio(0); } while (0)
; #define PG8_WAIT_V(n) asm volatile("s_waitcnt vmcnt(" #n ")" ::: "memory")
; #define PG8_WAIT_L(n) asm volatile("s_waitcnt lgkmcnt(" #n ")" ::: "memory")
; #define PG8_BAR __builtin_amdgcn_s_barrier()
; #define PG8_SCHED __builtin_amdgcn_sched_barrier(0)
; template <class Epi>
; __device__ __forceinline__ void gemm_phase(LAS unsigned char* lds, const Gemm g, const StaticOrder& S, const Epi& E) {
;     ...
;             PG8_LDB(B0, 0, 0); PG8_LDB(B1, 0, 1); PG8_SCHED; PG8_LDA(At, 0, 0); PG8_STAGE(PG8_SA(1, 1), a1 + hA, voffA);
;             PG8_WAIT_V(8); PG8_WAIT_L(0); PG8_BAR; PG8_MMA(0, 0, At, B0); PG8_MMA(0, 1, At, B1); PG8_BAR; PG8_SCHED;
;             PG8_LDA(At, 0, 1); PG8_STAGE(PG8_SB(0, 0), b2, voffB); PG8_STAGE(PG8_SB(0, 1), b2 + hB, voffB); PG8_STAGE(PG8_SA(0, 0), a2, voffA);
;             PG8_WAIT_V(8); PG8_WAIT_L(0); PG8_BAR; PG8_MMA(1, 0, At, B0); PG8_MMA(1, 1, At, B1); PG8_BAR; PG8_SCHED;
.LBB0_132:
	s_add_u32 s34, s8, 0xfffc0080
	s_addc_u32 s35, s9, -1
	s_add_i32 s42, 0, 0x10000
	s_cmp_eq_u32 s41, 12
	s_cselect_b32 s37, s7, s35
	s_cselect_b32 s36, s27, s34
	v_add_u32_e32 v153, s42, v139
	s_cselect_b32 s35, s25, s40
	s_cselect_b32 s34, s38, s39
	s_add_i32 s44, 0, 0x14000
	ds_read_b128 v[166:169], v153
	ds_read_b128 v[170:173], v153 offset:1024
	ds_read_b128 v[174:177], v153 offset:2048
	ds_read_b128 v[182:185], v153 offset:3072
	v_add_u32_e32 v153, s44, v139
	ds_read_b128 v[186:189], v153
	ds_read_b128 v[190:193], v153 offset:1024
	ds_read_b128 v[194:197], v153 offset:2048
	ds_read_b128 v[198:201], v153 offset:3072
	v_lshl_add_u64 v[178:179], s[8:9], 0, v[162:163]
	s_add_i32 m0, s19, 0xc000
	ds_read_b128 v[202:205], v149
	ds_read_b128 v[206:209], v149 offset:1024
	ds_read_b128 v[210:213], v149 offset:2048
	ds_read_b128 v[214:217], v149 offset:3072
	ds_read_b128 v[218:221], v149 offset:4096
	ds_read_b128 v[232:235], v149 offset:5120
	ds_read_b128 v[236:239], v149 offset:6144
	ds_read_b128 v[240:243], v149 offset:7168
	global_load_lds_dwordx4 v[178:179], off
	v_lshl_add_u64 v[178:179], s[8:9], 0, v[164:165]
	s_add_i32 m0, s19, 0xe000
	s_nop 0
	global_load_lds_dwordx4 v[178:179], off
	s_waitcnt vmcnt(8)
	s_waitcnt lgkmcnt(0)
	v_mfma_f32_16x16x32_bf16 v[126:129], v[166:169], v[202:205], v[126:129]
	v_mfma_f32_16x16x32_bf16 v[122:125], v[174:177], v[202:205], v[122:125]
	v_mfma_f32_16x16x32_bf16 v[110:113], v[166:169], v[210:213], v[110:113]
	v_mfma_f32_16x16x32_bf16 v[106:109], v[174:177], v[210:213], v[106:109]
	s_barrier
	s_setprio 1
	v_mfma_f32_16x16x32_bf16 v[94:97], v[166:169], v[218:221], v[94:97]
	v_mfma_f32_16x16x32_bf16 v[90:93], v[174:177], v[218:221], v[90:93]
	v_mfma_f32_16x16x32_bf16 v[78:81], v[166:169], v[236:239], v[78:81]
	v_mfma_f32_16x16x32_bf16 v[74:77], v[174:177], v[236:239], v[74:77]
	v_mfma_f32_16x16x32_bf16 v[126:129], v[170:173], v[206:209], v[126:129]
	v_mfma_f32_16x16x32_bf16 v[122:125], v[182:185], v[206:209], v[122:125]
	v_mfma_f32_16x16x32_bf16 v[110:113], v[170:173], v[214:217], v[110:113]
	v_mfma_f32_16x16x32_bf16 v[106:109], v[182:185], v[214:217], v[106:109]
	v_mfma_f32_16x16x32_bf16 v[94:97], v[170:173], v[232:235], v[94:97]
	v_mfma_f32_16x16x32_bf16 v[90:93], v[182:185], v[232:235], v[90:93]
	v_mfma_f32_16x16x32_bf16 v[78:81], v[170:173], v[240:243], v[78:81]
	v_mfma_f32_16x16x32_bf16 v[74:77], v[182:185], v[240:243], v[74:77]
	v_mfma_f32_16x16x32_bf16 v[118:121], v[186:189], v[202:205], v[118:121]
	v_mfma_f32_16x16x32_bf16 v[114:117], v[194:197], v[202:205], v[114:117]
	v_mfma_f32_16x16x32_bf16 v[102:105], v[186:189], v[210:213], v[102:105]
	v_mfma_f32_16x16x32_bf16 v[98:101], v[194:197], v[210:213], v[98:101]
	v_mfma_f32_16x16x32_bf16 v[86:89], v[186:189], v[218:221], v[86:89]
	v_mfma_f32_16x16x32_bf16 v[82:85], v[194:197], v[218:221], v[82:85]
	v_mfma_f32_16x16x32_bf16 v[70:73], v[186:189], v[236:239], v[70:73]
	v_mfma_f32_16x16x32_bf16 v[66:69], v[194:197], v[236:239], v[66:69]
	v_mfma_f32_16x16x32_bf16 v[118:121], v[190:193], v[206:209], v[118:121]
	v_mfma_f32_16x16x32_bf16 v[114:117], v[198:201], v[206:209], v[114:117]
	v_mfma_f32_16x16x32_bf16 v[102:105], v[190:193], v[214:217], v[102:105]
	v_mfma_f32_16x16x32_bf16 v[98:101], v[198:201], v[214:217], v[98:101]
	v_mfma_f32_16x16x32_bf16 v[86:89], v[190:193], v[232:235], v[86:89]
	v_mfma_f32_16x16x32_bf16 v[82:85], v[198:201], v[232:235], v[82:85]
	v_mfma_f32_16x16x32_bf16 v[70:73], v[190:193], v[240:243], v[70:73]
	v_mfma_f32_16x16x32_bf16 v[66:69], v[198:201], v[240:243], v[66:69]
	s_setprio 0
	s_barrier
	s_add_i32 s42, s42, s51
	v_lshl_add_u64 v[178:179], s[34:35], 0, v[132:133]
	s_mov_b32 m0, s42
	ds_read_b128 v[202:205], v149 offset:16384
	ds_read_b128 v[206:209], v149 offset:17408
	ds_read_b128 v[210:213], v149 offset:18432
	ds_read_b128 v[214:217], v149 offset:19456
	ds_read_b128 v[218:221], v149 offset:20480
	ds_read_b128 v[232:235], v149 offset:21504
	ds_read_b128 v[236:239], v149 offset:22528
	ds_read_b128 v[240:243], v149 offset:23552
	global_load_lds_dwordx4 v[178:179], off
	s_add_i32 m0, s42, 0x2000
	s_add_u32 s42, s34, 0x40000
	v_lshl_add_u64 v[244:245], s[34:35], 0, v[136:137]
	s_addc_u32 s43, s35, 0
	s_add_i32 s44, s44, s51
	global_load_lds_dwordx4 v[244:245], off
	v_lshl_add_u64 v[246:247], s[42:43], 0, v[132:133]
	s_mov_b32 m0, s44
	v_lshl_add_u64 v[248:249], s[36:37], 0, v[134:135]
	global_load_lds_dwordx4 v[246:247], off
	v_lshl_add_u64 v[246:247], s[42:43], 0, v[136:137]
	s_add_i32 m0, s44, 0x2000
	s_nop 0
	global_load_lds_dwordx4 v[246:247], off
	v_lshl_add_u64 v[246:247], s[36:37], 0, v[130:131]
	s_mov_b32 m0, s19
	s_nop 0
	global_load_lds_dwordx4 v[246:247], off
	s_mov_b32 m0, s56
	s_nop 0
	global_load_lds_dwordx4 v[248:249], off
	s_waitcnt vmcnt(8)
	s_waitcnt lgkmcnt(0)
	v_mfma_f32_16x16x32_bf16 v[62:65], v[166:169], v[202:205], v[62:65]
	v_mfma_f32_16x16x32_bf16 v[58:61], v[174:177], v[202:205], v[58:61]
	v_mfma_f32_16x16x32_bf16 v[46:49], v[166:169], v[210:213], v[46:49]
	v_mfma_f32_16x16x32_bf16 v[42:45], v[174:177], v[210:213], v[42:45]
	s_barrier
; #define PG8_STAGE(bufoff, gbase, voff) do { _Pragma("unroll") for (int _i = 0; _i < 2; ++_i) \
;         __builtin_amdgcn_global_load_lds((const unsigned*)((const char*)(gbase) + (voff)[_i]), (LAS unsigned*)(lds + (bufoff) + ldsw + _i * 8192), 16, 0, 0); } while (0)
; #define PG8_LDA(dst, b, h) do { _Pragma("unroll") for (int m = 0; m < 4; ++m) _Pragma("unroll") for (int k = 0; k < 2; ++k) dst[m][k] = *(const LAS bf16x8*)(lds + PG8_SA(b, h) + aoff + m * 2048 + k * 1024); } while (0)
; #define PG8_LDB(dst, b, h) do { _Pragma("unroll") for (int n = 0; n < 2; ++n) _Pragma("unroll") for (int k = 0; k < 2; ++k) dst[n][k] = *(const LAS bf16x8*)(lds + PG8_SB(b, h) + boff + n * 2048 + k * 1024); } while (0)
; #define PG8_MMA(ai, bj, At, Bt) do { __builtin_amdgcn_s_setprio(1); _Pragma("unroll") for (int m = 0; m < 4; ++m) _Pragma("unroll") for (int n = 0; n < 2; ++n) _Pragma("unroll") for (int k = 0; k < 2; ++k) \
;         acc[ai][bj][m][n] = __builtin_amdgcn_mfma_f32_16x16x32_bf16(Bt[n][k], At[m][k], acc[ai][bj][m][n], 0, 0, 0); __builtin_amdgcn_s_setprio(0); } while (0)
; #define PG8_WAIT_V(n) asm volatile("s_waitcnt vmcnt(" #n ")" ::: "memory")
; #define PG8_WAIT_L(n) asm volatile("s_waitcnt lgkmcnt(" #n ")" ::: "memory")
; #define PG8_BAR __builtin_amdgcn_s_barrier()
; #define PG8_SCHED __builtin_amdgcn_sched_barrier(0)
; template <class Epi>
; __device__ __forceinline__ void gemm_phase(LAS unsigned char* lds, const Gemm g, const StaticOrder& S, const Epi& E) {
;     ...
;             PG8_LDB(B0, 1, 0); PG8_LDB(B1, 1, 1); PG8_SCHED; PG8_LDA(At, 1, 0); PG8_STAGE(PG8_SA(0, 1), a2 + hA, voffA);
;             PG8_WAIT_V(8); PG8_WAIT_L(0); PG8_BAR; PG8_MMA(0, 0, At, B0); PG8_MMA(0, 1, At, B1); PG8_BAR; PG8_SCHED;
;             PG8_LDA(At, 1, 1); PG8_STAGE(PG8_SB(1, 0), b3, voffB); PG8_STAGE(PG8_SB(1, 1), b3 + hB, voffB); PG8_STAGE(PG8_SA(1, 0), a3, voffA);
;             PG8_WAIT_V(8); PG8_WAIT_L(0); PG8_BAR; PG8_MMA(1, 0, At, B0); PG8_MMA(1, 1, At, B1); PG8_BAR; PG8_SCHED;
	s_setprio 1
	v_mfma_f32_16x16x32_bf16 v[30:33], v[166:169], v[218:221], v[30:33]
	v_mfma_f32_16x16x32_bf16 v[26:29], v[174:177], v[218:221], v[26:29]
	v_mfma_f32_16x16x32_bf16 v[14:17], v[166:169], v[236:239], v[14:17]
	v_mfma_f32_16x16x32_bf16 v[10:13], v[174:177], v[236:239], v[10:13]
	v_mfma_f32_16x16x32_bf16 v[62:65], v[170:173], v[206:209], v[62:65]
	v_mfma_f32_16x16x32_bf16 v[58:61], v[182:185], v[206:209], v[58:61]
	v_mfma_f32_16x16x32_bf16 v[46:49], v[170:173], v[214:217], v[46:49]
	v_mfma_f32_16x16x32_bf16 v[42:45], v[182:185], v[214:217], v[42:45]
	v_mfma_f32_16x16x32_bf16 v[30:33], v[170:173], v[232:235], v[30:33]
	v_mfma_f32_16x16x32_bf16 v[26:29], v[182:185], v[232:235], v[26:29]
	v_mfma_f32_16x16x32_bf16 v[14:17], v[170:173], v[240:243], v[14:17]
	v_mfma_f32_16x16x32_bf16 v[10:13], v[182:185], v[240:243], v[10:13]
	v_mfma_f32_16x16x32_bf16 v[54:57], v[186:189], v[202:205], v[54:57]
	v_mfma_f32_16x16x32_bf16 v[50:53], v[194:197], v[202:205], v[50:53]
	v_mfma_f32_16x16x32_bf16 v[38:41], v[186:189], v[210:213], v[38:41]
	v_mfma_f32_16x16x32_bf16 v[34:37], v[194:197], v[210:213], v[34:37]
	v_mfma_f32_16x16x32_bf16 v[22:25], v[186:189], v[218:221], v[22:25]
	v_mfma_f32_16x16x32_bf16 v[18:21], v[194:197], v[218:221], v[18:21]
	v_mfma_f32_16x16x32_bf16 v[6:9], v[186:189], v[236:239], v[6:9]
	v_mfma_f32_16x16x32_bf16 v[2:5], v[194:197], v[236:239], v[2:5]
	v_mfma_f32_16x16x32_bf16 v[54:57], v[190:193], v[206:209], v[54:57]
	v_mfma_f32_16x16x32_bf16 v[50:53], v[198:201], v[206:209], v[50:53]
	v_mfma_f32_16x16x32_bf16 v[38:41], v[190:193], v[214:217], v[38:41]
	v_mfma_f32_16x16x32_bf16 v[34:37], v[198:201], v[214:217], v[34:37]
	v_mfma_f32_16x16x32_bf16 v[22:25], v[190:193], v[232:235], v[22:25]
	v_mfma_f32_16x16x32_bf16 v[18:21], v[198:201], v[232:235], v[18:21]
	v_mfma_f32_16x16x32_bf16 v[6:9], v[190:193], v[240:243], v[6:9]
	v_mfma_f32_16x16x32_bf16 v[2:5], v[198:201], v[240:243], v[2:5]
	s_setprio 0
	s_barrier
	s_add_i32 s42, 0, 0x18000
	v_add_u32_e32 v153, s42, v139
	s_add_i32 s43, 0, 0x1c000
	ds_read_b128 v[166:169], v153
	ds_read_b128 v[170:173], v153 offset:1024
	ds_read_b128 v[174:177], v153 offset:2048
	ds_read_b128 v[182:185], v153 offset:3072
	v_add_u32_e32 v153, s43, v139
	ds_read_b128 v[186:189], v153
	ds_read_b128 v[190:193], v153 offset:1024
	ds_read_b128 v[194:197], v153 offset:2048
	ds_read_b128 v[198:201], v153 offset:3072
	s_add_u32 s36, s36, 0x40000
	s_addc_u32 s37, s37, 0
	s_mov_b32 m0, s57
	v_lshl_add_u64 v[250:251], s[36:37], 0, v[130:131]
	ds_read_b128 v[202:205], v149 offset:32768
	ds_read_b128 v[206:209], v149 offset:33792
	ds_read_b128 v[210:213], v149 offset:34816
	ds_read_b128 v[214:217], v149 offset:35840
	ds_read_b128 v[218:221], v149 offset:36864
	ds_read_b128 v[232:235], v149 offset:37888
	ds_read_b128 v[236:239], v149 offset:38912
	ds_read_b128 v[240:243], v149 offset:39936
	global_load_lds_dwordx4 v[250:251], off
	v_lshl_add_u64 v[250:251], s[36:37], 0, v[134:135]
	s_mov_b32 m0, s58
	s_nop 0
	global_load_lds_dwordx4 v[250:251], off
	s_waitcnt vmcnt(8)
	s_waitcnt lgkmcnt(0)
	v_mfma_f32_16x16x32_bf16 v[126:129], v[166:169], v[202:205], v[126:129]
	v_mfma_f32_16x16x32_bf16 v[122:125], v[174:177], v[202:205], v[122:125]
	v_mfma_f32_16x16x32_bf16 v[110:113], v[166:169], v[210:213], v[110:113]
	v_mfma_f32_16x16x32_bf16 v[106:109], v[174:177], v[210:213], v[106:109]
	s_barrier
	s_setprio 1
	v_mfma_f32_16x16x32_bf16 v[94:97], v[166:169], v[218:221], v[94:97]
	v_mfma_f32_16x16x32_bf16 v[90:93], v[174:177], v[218:221], v[90:93]
	v_mfma_f32_16x16x32_bf16 v[78:81], v[166:169], v[236:239], v[78:81]
	v_mfma_f32_16x16x32_bf16 v[74:77], v[174:177], v[236:239], v[74:77]
	v_mfma_f32_16x16x32_bf16 v[126:129], v[170:173], v[206:209], v[126:129]
	v_mfma_f32_16x16x32_bf16 v[122:125], v[182:185], v[206:209], v[122:125]
	v_mfma_f32_16x16x32_bf16 v[110:113], v[170:173], v[214:217], v[110:113]
	v_mfma_f32_16x16x32_bf16 v[106:109], v[182:185], v[214:217], v[106:109]
	v_mfma_f32_16x16x32_bf16 v[94:97], v[170:173], v[232:235], v[94:97]
	v_mfma_f32_16x16x32_bf16 v[90:93], v[182:185], v[232:235], v[90:93]
	v_mfma_f32_16x16x32_bf16 v[78:81], v[170:173], v[240:243], v[78:81]
	v_mfma_f32_16x16x32_bf16 v[74:77], v[182:185], v[240:243], v[74:77]
	v_mfma_f32_16x16x32_bf16 v[118:121], v[186:189], v[202:205], v[118:121]
	v_mfma_f32_16x16x32_bf16 v[114:117], v[194:197], v[202:205], v[114:117]
	v_mfma_f32_16x16x32_bf16 v[102:105], v[186:189], v[210:213], v[102:105]
	v_mfma_f32_16x16x32_bf16 v[98:101], v[194:197], v[210:213], v[98:101]
	v_mfma_f32_16x16x32_bf16 v[86:89], v[186:189], v[218:221], v[86:89]
	v_mfma_f32_16x16x32_bf16 v[82:85], v[194:197], v[218:221], v[82:85]
	v_mfma_f32_16x16x32_bf16 v[70:73], v[186:189], v[236:239], v[70:73]
	v_mfma_f32_16x16x32_bf16 v[66:69], v[194:197], v[236:239], v[66:69]
	v_mfma_f32_16x16x32_bf16 v[118:121], v[190:193], v[206:209], v[118:121]
	v_mfma_f32_16x16x32_bf16 v[114:117], v[198:201], v[206:209], v[114:117]
	v_mfma_f32_16x16x32_bf16 v[102:105], v[190:193], v[214:217], v[102:105]
	v_mfma_f32_16x16x32_bf16 v[98:101], v[198:201], v[214:217], v[98:101]
	v_mfma_f32_16x16x32_bf16 v[86:89], v[190:193], v[232:235], v[86:89]
	v_mfma_f32_16x16x32_bf16 v[82:85], v[198:201], v[232:235], v[82:85]
	v_mfma_f32_16x16x32_bf16 v[70:73], v[190:193], v[240:243], v[70:73]
	v_mfma_f32_16x16x32_bf16 v[66:69], v[198:201], v[240:243], v[66:69]
	s_setprio 0
	s_barrier
; #define PG8_STAGE(bufoff, gbase, voff) do { _Pragma("unroll") for (int _i = 0; _i < 2; ++_i) \
;         __builtin_amdgcn_global_load_lds((const unsigned*)((const char*)(gbase) + (voff)[_i]), (LAS unsigned*)(lds + (bufoff) + ldsw + _i * 8192), 16, 0, 0); } while (0)
; #define PG8_LDA(dst, b, h) do { _Pragma("unroll") for (int m = 0; m < 4; ++m) _Pragma("unroll") for (int k = 0; k < 2; ++k) dst[m][k] = *(const LAS bf16x8*)(lds + PG8_SA(b, h) + aoff + m * 2048 + k * 1024); } while (0)
; #define PG8_MMA(ai, bj, At, Bt) do { __builtin_amdgcn_s_setprio(1); _Pragma("unroll") for (int m = 0; m < 4; ++m) _Pragma("unroll") for (int n = 0; n < 2; ++n) _Pragma("unroll") for (int k = 0; k < 2; ++k) \
;         acc[ai][bj][m][n] = __builtin_amdgcn_mfma_f32_16x16x32_bf16(Bt[n][k], At[m][k], acc[ai][bj][m][n], 0, 0, 0); __builtin_amdgcn_s_setprio(0); } while (0)
; #define PG8_WAIT_V(n) asm volatile("s_waitcnt vmcnt(" #n ")" ::: "memory")
; #define PG8_WAIT_L(n) asm volatile("s_waitcnt lgkmcnt(" #n ")" ::: "memory")
; #define PG8_BAR __builtin_amdgcn_s_barrier()
; #define PG8_SCHED __builtin_amdgcn_sched_barrier(0)
; template <class Epi>
; __device__ __forceinline__ void gemm_phase(LAS unsigned char* lds, const Gemm g, const StaticOrder& S, const Epi& E) {
;     ...
;             PG8_LDA(At, 1, 1); PG8_STAGE(PG8_SB(1, 0), b3, voffB); PG8_STAGE(PG8_SB(1, 1), b3 + hB, voffB); PG8_STAGE(PG8_SA(1, 0), a3, voffA);
;             PG8_WAIT_V(8); PG8_WAIT_L(0); PG8_BAR; PG8_MMA(1, 0, At, B0); PG8_MMA(1, 1, At, B1); PG8_BAR; PG8_SCHED;
;         }
;         if (wr == 0) PG8_BAR;
	s_add_i32 s36, s42, s51
	v_lshl_add_u64 v[178:179], v[178:179], 0, s[88:89]
	s_mov_b32 m0, s36
	ds_read_b128 v[202:205], v149 offset:49152
	ds_read_b128 v[206:209], v149 offset:50176
	ds_read_b128 v[210:213], v149 offset:51200
	ds_read_b128 v[214:217], v149 offset:52224
	ds_read_b128 v[218:221], v149 offset:53248
	ds_read_b128 v[232:235], v149 offset:54272
	ds_read_b128 v[236:239], v149 offset:55296
	ds_read_b128 v[240:243], v149 offset:56320
	global_load_lds_dwordx4 v[178:179], off
	s_add_i32 m0, s36, 0x2000
	s_add_u32 s34, s34, 0x40080
	v_lshl_add_u64 v[178:179], v[244:245], 0, s[88:89]
	s_addc_u32 s35, s35, 0
	s_add_i32 s36, s43, s51
	global_load_lds_dwordx4 v[178:179], off
	v_lshl_add_u64 v[178:179], s[34:35], 0, v[132:133]
	s_mov_b32 m0, s36
	s_nop 0
	global_load_lds_dwordx4 v[178:179], off
	v_lshl_add_u64 v[178:179], s[34:35], 0, v[136:137]
	s_add_i32 m0, s36, 0x2000
	s_nop 0
	global_load_lds_dwordx4 v[178:179], off
	v_lshl_add_u64 v[178:179], v[246:247], 0, s[88:89]
	s_mov_b32 m0, s60
	s_nop 0
	global_load_lds_dwordx4 v[178:179], off
	v_lshl_add_u64 v[178:179], v[248:249], 0, s[88:89]
	s_mov_b32 m0, s61
	s_nop 0
	global_load_lds_dwordx4 v[178:179], off
	s_waitcnt vmcnt(8)
	s_waitcnt lgkmcnt(0)
	v_mfma_f32_16x16x32_bf16 v[62:65], v[166:169], v[202:205], v[62:65]
	v_mfma_f32_16x16x32_bf16 v[58:61], v[174:177], v[202:205], v[58:61]
	v_mfma_f32_16x16x32_bf16 v[46:49], v[166:169], v[210:213], v[46:49]
	v_mfma_f32_16x16x32_bf16 v[42:45], v[174:177], v[210:213], v[42:45]
	s_barrier
	s_setprio 1
	v_mfma_f32_16x16x32_bf16 v[30:33], v[166:169], v[218:221], v[30:33]
	v_mfma_f32_16x16x32_bf16 v[26:29], v[174:177], v[218:221], v[26:29]
	v_mfma_f32_16x16x32_bf16 v[14:17], v[166:169], v[236:239], v[14:17]
	v_mfma_f32_16x16x32_bf16 v[10:13], v[174:177], v[236:239], v[10:13]
	v_mfma_f32_16x16x32_bf16 v[62:65], v[170:173], v[206:209], v[62:65]
	v_mfma_f32_16x16x32_bf16 v[58:61], v[182:185], v[206:209], v[58:61]
	v_mfma_f32_16x16x32_bf16 v[46:49], v[170:173], v[214:217], v[46:49]
	v_mfma_f32_16x16x32_bf16 v[42:45], v[182:185], v[214:217], v[42:45]
	v_mfma_f32_16x16x32_bf16 v[30:33], v[170:173], v[232:235], v[30:33]
	v_mfma_f32_16x16x32_bf16 v[26:29], v[182:185], v[232:235], v[26:29]
	v_mfma_f32_16x16x32_bf16 v[14:17], v[170:173], v[240:243], v[14:17]
	v_mfma_f32_16x16x32_bf16 v[10:13], v[182:185], v[240:243], v[10:13]
	v_mfma_f32_16x16x32_bf16 v[54:57], v[186:189], v[202:205], v[54:57]
	v_mfma_f32_16x16x32_bf16 v[50:53], v[194:197], v[202:205], v[50:53]
	v_mfma_f32_16x16x32_bf16 v[38:41], v[186:189], v[210:213], v[38:41]
	v_mfma_f32_16x16x32_bf16 v[34:37], v[194:197], v[210:213], v[34:37]
	v_mfma_f32_16x16x32_bf16 v[22:25], v[186:189], v[218:221], v[22:25]
	v_mfma_f32_16x16x32_bf16 v[18:21], v[194:197], v[218:221], v[18:21]
	v_mfma_f32_16x16x32_bf16 v[6:9], v[186:189], v[236:239], v[6:9]
	v_mfma_f32_16x16x32_bf16 v[2:5], v[194:197], v[236:239], v[2:5]
	v_mfma_f32_16x16x32_bf16 v[54:57], v[190:193], v[206:209], v[54:57]
	v_mfma_f32_16x16x32_bf16 v[50:53], v[198:201], v[206:209], v[50:53]
	v_mfma_f32_16x16x32_bf16 v[38:41], v[190:193], v[214:217], v[38:41]
	v_mfma_f32_16x16x32_bf16 v[34:37], v[198:201], v[214:217], v[34:37]
	v_mfma_f32_16x16x32_bf16 v[22:25], v[190:193], v[232:235], v[22:25]
	v_mfma_f32_16x16x32_bf16 v[18:21], v[198:201], v[232:235], v[18:21]
	v_mfma_f32_16x16x32_bf16 v[6:9], v[190:193], v[240:243], v[6:9]
	v_mfma_f32_16x16x32_bf16 v[2:5], v[198:201], v[240:243], v[2:5]
	s_setprio 0
	s_barrier
	s_add_i32 s41, s41, 2
	s_add_u32 s8, s8, 0x100
	s_addc_u32 s9, s9, 0
	s_add_u32 s39, s39, 0x100
	s_addc_u32 s40, s40, 0
	s_cmp_gt_u32 s41, 13
	s_cbranch_scc0 .LBB0_132
	s_and_b64 vcc, exec, s[16:17]
	s_cbranch_vccz .LBB0_135
	s_barrier

; #define PG8_STAGE(bufoff, gbase, voff) do { _Pragma("unroll") for (int _i = 0; _i < 2; ++_i) \
;         __builtin_amdgcn_global_load_lds((const unsigned*)((const char*)(gbase) + (voff)[_i]), (LAS unsigned*)(lds + (bufoff) + ldsw + _i * 8192), 16, 0, 0); } while (0)
; #define PG8_LDA(dst, b, h) do { _Pragma("unroll") for (int m = 0; m < 4; ++m) _Pragma("unroll") for (int k = 0; k < 2; ++k) dst[m][k] = *(const LAS bf16x8*)(lds + PG8_SA(b, h) + aoff + m * 2048 + k * 1024); } while (0)
; #define PG8_LDB(dst, b, h) do { _Pragma("unroll") for (int n = 0; n < 2; ++n) _Pragma("unroll") for (int k = 0; k < 2; ++k) dst[n][k] = *(const LAS bf16x8*)(lds + PG8_SB(b, h) + boff + n * 2048 + k * 1024); } while (0)
; #define PG8_MMA(ai, bj, At, Bt) do { __builtin_amdgcn_s_setprio(1); _Pragma("unroll") for (int m = 0; m < 4; ++m) _Pragma("unroll") for (int n = 0; n < 2; ++n) _Pragma("unroll") for (int k = 0; k < 2; ++k) \
;         acc[ai][bj][m][n] = __builtin_amdgcn_mfma_f32_16x16x32_bf16(Bt[n][k], At[m][k], acc[ai][bj][m][n], 0, 0, 0); __builtin_amdgcn_s_setprio(0); } while (0)
; #define PG8_WAIT_V(n) asm volatile("s_waitcnt vmcnt(" #n ")" ::: "memory")
; #define PG8_WAIT_L(n) asm volatile("s_waitcnt lgkmcnt(" #n ")" ::: "memory")
; #define PG8_BAR __builtin_amdgcn_s_barrier()
; #define PG8_SCHED __builtin_amdgcn_sched_barrier(0)
; template <class Epi>
; __device__ __forceinline__ void gemm_phase(LAS unsigned char* lds, const Gemm g, const StaticOrder& S, const Epi& E) {
;     ...
;             PG8_LDB(B0, 0, 0); PG8_LDB(B1, 0, 1); PG8_SCHED; PG8_LDA(At, 0, 0); PG8_STAGE(PG8_SA(1, 1), a1 + hA, voffA);
;             PG8_WAIT_V(8); PG8_WAIT_L(0); PG8_BAR; PG8_MMA(0, 0, At, B0); PG8_MMA(0, 1, At, B1); PG8_BAR; PG8_SCHED;
;             PG8_LDA(At, 0, 1); PG8_STAGE(PG8_SB(0, 0), b2, voffB); PG8_STAGE(PG8_SB(0, 1), b2 + hB, voffB); PG8_STAGE(PG8_SA(0, 0), a2, voffA);
;             PG8_WAIT_V(8); PG8_WAIT_L(0); PG8_BAR; PG8_MMA(1, 0, At, B0); PG8_MMA(1, 1, At, B1); PG8_BAR; PG8_SCHED;
.LBB0_518:
	s_add_u32 s30, s28, 0xfffc0080
	s_addc_u32 s31, s29, -1
	s_add_i32 s71, 0, 0x10000
	s_cmp_eq_u32 s70, 28
	s_cselect_b32 s35, s21, s31
	s_cselect_b32 s34, s27, s30
	v_add_u32_e32 v154, s71, v156
	s_cselect_b32 s31, s19, s67
	s_cselect_b32 s30, s65, s66
	s_add_i32 s73, 0, 0x14000
	ds_read_b128 v[98:101], v154
	ds_read_b128 v[102:105], v154 offset:1024
	ds_read_b128 v[158:161], v154 offset:2048
	ds_read_b128 v[162:165], v154 offset:3072
	v_add_u32_e32 v154, s73, v156
	ds_read_b128 v[166:169], v154
	ds_read_b128 v[170:173], v154 offset:1024
	ds_read_b128 v[174:177], v154 offset:2048
	ds_read_b128 v[182:185], v154 offset:3072
	v_lshl_add_u64 v[154:155], s[28:29], 0, v[150:151]
	s_add_i32 m0, s54, 0xc000
	ds_read_b128 v[186:189], v157
	ds_read_b128 v[190:193], v157 offset:1024
	ds_read_b128 v[194:197], v157 offset:2048
	ds_read_b128 v[198:201], v157 offset:3072
	ds_read_b128 v[202:205], v157 offset:4096
	ds_read_b128 v[206:209], v157 offset:5120
	ds_read_b128 v[210:213], v157 offset:6144
	ds_read_b128 v[214:217], v157 offset:7168
	global_load_lds_dwordx4 v[154:155], off
	v_lshl_add_u64 v[154:155], s[28:29], 0, v[152:153]
	s_add_i32 m0, s54, 0xe000
	s_nop 0
	global_load_lds_dwordx4 v[154:155], off
	s_waitcnt vmcnt(8)
	s_waitcnt lgkmcnt(0)
	v_mfma_f32_16x16x32_bf16 v[134:137], v[98:101], v[186:189], v[134:137]
	v_mfma_f32_16x16x32_bf16 v[130:133], v[158:161], v[186:189], v[130:133]
	v_mfma_f32_16x16x32_bf16 v[126:129], v[98:101], v[194:197], v[126:129]
	v_mfma_f32_16x16x32_bf16 v[122:125], v[158:161], v[194:197], v[122:125]
	s_barrier
	s_setprio 1
	v_mfma_f32_16x16x32_bf16 v[118:121], v[98:101], v[202:205], v[118:121]
	v_mfma_f32_16x16x32_bf16 v[114:117], v[158:161], v[202:205], v[114:117]
	v_mfma_f32_16x16x32_bf16 v[110:113], v[98:101], v[210:213], v[110:113]
	v_mfma_f32_16x16x32_bf16 v[106:109], v[158:161], v[210:213], v[106:109]
	v_mfma_f32_16x16x32_bf16 v[134:137], v[102:105], v[190:193], v[134:137]
	v_mfma_f32_16x16x32_bf16 v[130:133], v[162:165], v[190:193], v[130:133]
	v_mfma_f32_16x16x32_bf16 v[126:129], v[102:105], v[198:201], v[126:129]
	v_mfma_f32_16x16x32_bf16 v[122:125], v[162:165], v[198:201], v[122:125]
	v_mfma_f32_16x16x32_bf16 v[118:121], v[102:105], v[206:209], v[118:121]
	v_mfma_f32_16x16x32_bf16 v[114:117], v[162:165], v[206:209], v[114:117]
	v_mfma_f32_16x16x32_bf16 v[110:113], v[102:105], v[214:217], v[110:113]
	v_mfma_f32_16x16x32_bf16 v[106:109], v[162:165], v[214:217], v[106:109]
	v_mfma_f32_16x16x32_bf16 v[62:65], v[166:169], v[186:189], v[62:65]
	v_mfma_f32_16x16x32_bf16 v[58:61], v[174:177], v[186:189], v[58:61]
	v_mfma_f32_16x16x32_bf16 v[54:57], v[166:169], v[194:197], v[54:57]
	v_mfma_f32_16x16x32_bf16 v[50:53], v[174:177], v[194:197], v[50:53]
	v_mfma_f32_16x16x32_bf16 v[46:49], v[166:169], v[202:205], v[46:49]
	v_mfma_f32_16x16x32_bf16 v[42:45], v[174:177], v[202:205], v[42:45]
	v_mfma_f32_16x16x32_bf16 v[38:41], v[166:169], v[210:213], v[38:41]
	v_mfma_f32_16x16x32_bf16 v[34:37], v[174:177], v[210:213], v[34:37]
	v_mfma_f32_16x16x32_bf16 v[62:65], v[170:173], v[190:193], v[62:65]
	v_mfma_f32_16x16x32_bf16 v[58:61], v[182:185], v[190:193], v[58:61]
	v_mfma_f32_16x16x32_bf16 v[54:57], v[170:173], v[198:201], v[54:57]
	v_mfma_f32_16x16x32_bf16 v[50:53], v[182:185], v[198:201], v[50:53]
	v_mfma_f32_16x16x32_bf16 v[46:49], v[170:173], v[206:209], v[46:49]
	v_mfma_f32_16x16x32_bf16 v[42:45], v[182:185], v[206:209], v[42:45]
	v_mfma_f32_16x16x32_bf16 v[38:41], v[170:173], v[214:217], v[38:41]
	v_mfma_f32_16x16x32_bf16 v[34:37], v[182:185], v[214:217], v[34:37]
	s_setprio 0
	s_barrier
	s_add_i32 s71, s71, s53
	v_lshl_add_u64 v[154:155], s[30:31], 0, v[140:141]
	s_mov_b32 m0, s71
	ds_read_b128 v[186:189], v157 offset:16384
	ds_read_b128 v[190:193], v157 offset:17408
	ds_read_b128 v[194:197], v157 offset:18432
	ds_read_b128 v[198:201], v157 offset:19456
	ds_read_b128 v[202:205], v157 offset:20480
	ds_read_b128 v[206:209], v157 offset:21504
	ds_read_b128 v[210:213], v157 offset:22528
	ds_read_b128 v[214:217], v157 offset:23552
	global_load_lds_dwordx4 v[154:155], off
	s_add_i32 m0, s71, 0x2000
	s_add_u32 s74, s30, 0x80000
	v_lshl_add_u64 v[178:179], s[30:31], 0, v[144:145]
	s_addc_u32 s75, s31, 0
	s_add_i32 s71, s73, s53
	global_load_lds_dwordx4 v[178:179], off
	v_lshl_add_u64 v[218:219], s[74:75], 0, v[140:141]
	s_mov_b32 m0, s71
	v_lshl_add_u64 v[220:221], s[34:35], 0, v[142:143]
	global_load_lds_dwordx4 v[218:219], off
	v_lshl_add_u64 v[218:219], s[74:75], 0, v[144:145]
	s_add_i32 m0, s71, 0x2000
	s_nop 0
	global_load_lds_dwordx4 v[218:219], off
	v_lshl_add_u64 v[218:219], s[34:35], 0, v[138:139]
	s_mov_b32 m0, s54
	s_nop 0
	global_load_lds_dwordx4 v[218:219], off
	s_mov_b32 m0, s55
	s_nop 0
	global_load_lds_dwordx4 v[220:221], off
	s_waitcnt vmcnt(8)
	s_waitcnt lgkmcnt(0)
	v_mfma_f32_16x16x32_bf16 v[94:97], v[98:101], v[186:189], v[94:97]
	v_mfma_f32_16x16x32_bf16 v[90:93], v[158:161], v[186:189], v[90:93]
	v_mfma_f32_16x16x32_bf16 v[86:89], v[98:101], v[194:197], v[86:89]
	v_mfma_f32_16x16x32_bf16 v[82:85], v[158:161], v[194:197], v[82:85]
	s_barrier
; #define PG8_STAGE(bufoff, gbase, voff) do { _Pragma("unroll") for (int _i = 0; _i < 2; ++_i) \
;         __builtin_amdgcn_global_load_lds((const unsigned*)((const char*)(gbase) + (voff)[_i]), (LAS unsigned*)(lds + (bufoff) + ldsw + _i * 8192), 16, 0, 0); } while (0)
; #define PG8_LDA(dst, b, h) do { _Pragma("unroll") for (int m = 0; m < 4; ++m) _Pragma("unroll") for (int k = 0; k < 2; ++k) dst[m][k] = *(const LAS bf16x8*)(lds + PG8_SA(b, h) + aoff + m * 2048 + k * 1024); } while (0)
; #define PG8_LDB(dst, b, h) do { _Pragma("unroll") for (int n = 0; n < 2; ++n) _Pragma("unroll") for (int k = 0; k < 2; ++k) dst[n][k] = *(const LAS bf16x8*)(lds + PG8_SB(b, h) + boff + n * 2048 + k * 1024); } while (0)
; #define PG8_MMA(ai, bj, At, Bt) do { __builtin_amdgcn_s_setprio(1); _Pragma("unroll") for (int m = 0; m < 4; ++m) _Pragma("unroll") for (int n = 0; n < 2; ++n) _Pragma("unroll") for (int k = 0; k < 2; ++k) \
;         acc[ai][bj][m][n] = __builtin_amdgcn_mfma_f32_16x16x32_bf16(Bt[n][k], At[m][k], acc[ai][bj][m][n], 0, 0, 0); __builtin_amdgcn_s_setprio(0); } while (0)
; #define PG8_WAIT_V(n) asm volatile("s_waitcnt vmcnt(" #n ")" ::: "memory")
; #define PG8_WAIT_L(n) asm volatile("s_waitcnt lgkmcnt(" #n ")" ::: "memory")
; #define PG8_BAR __builtin_amdgcn_s_barrier()
; #define PG8_SCHED __builtin_amdgcn_sched_barrier(0)
; template <class Epi>
; __device__ __forceinline__ void gemm_phase(LAS unsigned char* lds, const Gemm g, const StaticOrder& S, const Epi& E) {
;     ...
;             PG8_WAIT_V(8); PG8_WAIT_L(0); PG8_BAR; PG8_MMA(1, 0, At, B0); PG8_MMA(1, 1, At, B1); PG8_BAR; PG8_SCHED;
;             PG8_LDB(B0, 1, 0); PG8_LDB(B1, 1, 1); PG8_SCHED; PG8_LDA(At, 1, 0); PG8_STAGE(PG8_SA(0, 1), a2 + hA, voffA);
;             PG8_WAIT_V(8); PG8_WAIT_L(0); PG8_BAR; PG8_MMA(0, 0, At, B0); PG8_MMA(0, 1, At, B1); PG8_BAR; PG8_SCHED;
	s_setprio 1
	v_mfma_f32_16x16x32_bf16 v[78:81], v[98:101], v[202:205], v[78:81]
	v_mfma_f32_16x16x32_bf16 v[74:77], v[158:161], v[202:205], v[74:77]
	v_mfma_f32_16x16x32_bf16 v[70:73], v[98:101], v[210:213], v[70:73]
	v_mfma_f32_16x16x32_bf16 v[66:69], v[158:161], v[210:213], v[66:69]
	v_mfma_f32_16x16x32_bf16 v[94:97], v[102:105], v[190:193], v[94:97]
	v_mfma_f32_16x16x32_bf16 v[90:93], v[162:165], v[190:193], v[90:93]
	v_mfma_f32_16x16x32_bf16 v[86:89], v[102:105], v[198:201], v[86:89]
	v_mfma_f32_16x16x32_bf16 v[82:85], v[162:165], v[198:201], v[82:85]
	v_mfma_f32_16x16x32_bf16 v[78:81], v[102:105], v[206:209], v[78:81]
	v_mfma_f32_16x16x32_bf16 v[74:77], v[162:165], v[206:209], v[74:77]
	v_mfma_f32_16x16x32_bf16 v[70:73], v[102:105], v[214:217], v[70:73]
	v_mfma_f32_16x16x32_bf16 v[66:69], v[162:165], v[214:217], v[66:69]
	v_mfma_f32_16x16x32_bf16 v[30:33], v[166:169], v[186:189], v[30:33]
	v_mfma_f32_16x16x32_bf16 v[26:29], v[174:177], v[186:189], v[26:29]
	v_mfma_f32_16x16x32_bf16 v[22:25], v[166:169], v[194:197], v[22:25]
	v_mfma_f32_16x16x32_bf16 v[18:21], v[174:177], v[194:197], v[18:21]
	v_mfma_f32_16x16x32_bf16 v[14:17], v[166:169], v[202:205], v[14:17]
	v_mfma_f32_16x16x32_bf16 v[10:13], v[174:177], v[202:205], v[10:13]
	v_mfma_f32_16x16x32_bf16 v[6:9], v[166:169], v[210:213], v[6:9]
	v_mfma_f32_16x16x32_bf16 v[2:5], v[174:177], v[210:213], v[2:5]
	v_mfma_f32_16x16x32_bf16 v[30:33], v[170:173], v[190:193], v[30:33]
	v_mfma_f32_16x16x32_bf16 v[26:29], v[182:185], v[190:193], v[26:29]
	v_mfma_f32_16x16x32_bf16 v[22:25], v[170:173], v[198:201], v[22:25]
	v_mfma_f32_16x16x32_bf16 v[18:21], v[182:185], v[198:201], v[18:21]
	v_mfma_f32_16x16x32_bf16 v[14:17], v[170:173], v[206:209], v[14:17]
	v_mfma_f32_16x16x32_bf16 v[10:13], v[182:185], v[206:209], v[10:13]
	v_mfma_f32_16x16x32_bf16 v[6:9], v[170:173], v[214:217], v[6:9]
	v_mfma_f32_16x16x32_bf16 v[2:5], v[182:185], v[214:217], v[2:5]
	s_setprio 0
	s_barrier
	s_add_i32 s71, 0, 0x18000
	s_add_i32 s73, 0, 0x1c000
	v_add_u32_e32 v162, s71, v156
	v_add_u32_e32 v180, s73, v156
	ds_read_b128 v[98:101], v162
	ds_read_b128 v[102:105], v162 offset:1024
	ds_read_b128 v[158:161], v162 offset:2048
	ds_read_b128 v[162:165], v162 offset:3072
	ds_read_b128 v[166:169], v180
	ds_read_b128 v[170:173], v180 offset:1024
	ds_read_b128 v[174:177], v180 offset:2048
	ds_read_b128 v[182:185], v180 offset:3072
	s_add_u32 s34, s34, 0x40000
	s_addc_u32 s35, s35, 0
	s_mov_b32 m0, s56
	v_lshl_add_u64 v[232:233], s[34:35], 0, v[138:139]
	ds_read_b128 v[186:189], v157 offset:32768
	ds_read_b128 v[190:193], v157 offset:33792
	ds_read_b128 v[194:197], v157 offset:34816
	ds_read_b128 v[198:201], v157 offset:35840
	ds_read_b128 v[202:205], v157 offset:36864
	ds_read_b128 v[206:209], v157 offset:37888
	ds_read_b128 v[210:213], v157 offset:38912
	ds_read_b128 v[214:217], v157 offset:39936
	global_load_lds_dwordx4 v[232:233], off
	v_lshl_add_u64 v[232:233], s[34:35], 0, v[142:143]
	s_mov_b32 m0, s57
	s_nop 0
	global_load_lds_dwordx4 v[232:233], off
	s_waitcnt vmcnt(8)
	s_waitcnt lgkmcnt(0)
	v_mfma_f32_16x16x32_bf16 v[134:137], v[98:101], v[186:189], v[134:137]
	v_mfma_f32_16x16x32_bf16 v[130:133], v[158:161], v[186:189], v[130:133]
	v_mfma_f32_16x16x32_bf16 v[126:129], v[98:101], v[194:197], v[126:129]
	v_mfma_f32_16x16x32_bf16 v[122:125], v[158:161], v[194:197], v[122:125]
	s_barrier
	s_setprio 1
	v_mfma_f32_16x16x32_bf16 v[118:121], v[98:101], v[202:205], v[118:121]
	v_mfma_f32_16x16x32_bf16 v[114:117], v[158:161], v[202:205], v[114:117]
	v_mfma_f32_16x16x32_bf16 v[110:113], v[98:101], v[210:213], v[110:113]
	v_mfma_f32_16x16x32_bf16 v[106:109], v[158:161], v[210:213], v[106:109]
	v_mfma_f32_16x16x32_bf16 v[134:137], v[102:105], v[190:193], v[134:137]
	v_mfma_f32_16x16x32_bf16 v[130:133], v[162:165], v[190:193], v[130:133]
	v_mfma_f32_16x16x32_bf16 v[126:129], v[102:105], v[198:201], v[126:129]
	v_mfma_f32_16x16x32_bf16 v[122:125], v[162:165], v[198:201], v[122:125]
	v_mfma_f32_16x16x32_bf16 v[118:121], v[102:105], v[206:209], v[118:121]
	v_mfma_f32_16x16x32_bf16 v[114:117], v[162:165], v[206:209], v[114:117]
	v_mfma_f32_16x16x32_bf16 v[110:113], v[102:105], v[214:217], v[110:113]
	v_mfma_f32_16x16x32_bf16 v[106:109], v[162:165], v[214:217], v[106:109]
	v_mfma_f32_16x16x32_bf16 v[62:65], v[166:169], v[186:189], v[62:65]
	v_mfma_f32_16x16x32_bf16 v[58:61], v[174:177], v[186:189], v[58:61]
	v_mfma_f32_16x16x32_bf16 v[54:57], v[166:169], v[194:197], v[54:57]
	v_mfma_f32_16x16x32_bf16 v[50:53], v[174:177], v[194:197], v[50:53]
	v_mfma_f32_16x16x32_bf16 v[46:49], v[166:169], v[202:205], v[46:49]
	v_mfma_f32_16x16x32_bf16 v[42:45], v[174:177], v[202:205], v[42:45]
	v_mfma_f32_16x16x32_bf16 v[38:41], v[166:169], v[210:213], v[38:41]
	v_mfma_f32_16x16x32_bf16 v[34:37], v[174:177], v[210:213], v[34:37]
	v_mfma_f32_16x16x32_bf16 v[62:65], v[170:173], v[190:193], v[62:65]
	v_mfma_f32_16x16x32_bf16 v[58:61], v[182:185], v[190:193], v[58:61]
	v_mfma_f32_16x16x32_bf16 v[54:57], v[170:173], v[198:201], v[54:57]
	v_mfma_f32_16x16x32_bf16 v[50:53], v[182:185], v[198:201], v[50:53]
	v_mfma_f32_16x16x32_bf16 v[46:49], v[170:173], v[206:209], v[46:49]
	v_mfma_f32_16x16x32_bf16 v[42:45], v[182:185], v[206:209], v[42:45]
	v_mfma_f32_16x16x32_bf16 v[38:41], v[170:173], v[214:217], v[38:41]
	v_mfma_f32_16x16x32_bf16 v[34:37], v[182:185], v[214:217], v[34:37]
	s_setprio 0
	s_barrier
; #define PG8_STAGE(bufoff, gbase, voff) do { _Pragma("unroll") for (int _i = 0; _i < 2; ++_i) \
;         __builtin_amdgcn_global_load_lds((const unsigned*)((const char*)(gbase) + (voff)[_i]), (LAS unsigned*)(lds + (bufoff) + ldsw + _i * 8192), 16, 0, 0); } while (0)
; #define PG8_LDA(dst, b, h) do { _Pragma("unroll") for (int m = 0; m < 4; ++m) _Pragma("unroll") for (int k = 0; k < 2; ++k) dst[m][k] = *(const LAS bf16x8*)(lds + PG8_SA(b, h) + aoff + m * 2048 + k * 1024); } while (0)
; #define PG8_MMA(ai, bj, At, Bt) do { __builtin_amdgcn_s_setprio(1); _Pragma("unroll") for (int m = 0; m < 4; ++m) _Pragma("unroll") for (int n = 0; n < 2; ++n) _Pragma("unroll") for (int k = 0; k < 2; ++k) \
;         acc[ai][bj][m][n] = __builtin_amdgcn_mfma_f32_16x16x32_bf16(Bt[n][k], At[m][k], acc[ai][bj][m][n], 0, 0, 0); __builtin_amdgcn_s_setprio(0); } while (0)
; #define PG8_WAIT_V(n) asm volatile("s_waitcnt vmcnt(" #n ")" ::: "memory")
; #define PG8_WAIT_L(n) asm volatile("s_waitcnt lgkmcnt(" #n ")" ::: "memory")
; #define PG8_BAR __builtin_amdgcn_s_barrier()
; #define PG8_SCHED __builtin_amdgcn_sched_barrier(0)
; template <class Epi>
; __device__ __forceinline__ void gemm_phase(LAS unsigned char* lds, const Gemm g, const StaticOrder& S, const Epi& E) {
;     ...
;             PG8_LDA(At, 1, 1); PG8_STAGE(PG8_SB(1, 0), b3, voffB); PG8_STAGE(PG8_SB(1, 1), b3 + hB, voffB); PG8_STAGE(PG8_SA(1, 0), a3, voffA);
;             PG8_WAIT_V(8); PG8_WAIT_L(0); PG8_BAR; PG8_MMA(1, 0, At, B0); PG8_MMA(1, 1, At, B1); PG8_BAR; PG8_SCHED;
;         }
;         if (wr == 0) PG8_BAR;
	s_add_i32 s34, s71, s53
	v_lshl_add_u64 v[154:155], v[154:155], 0, s[88:89]
	s_mov_b32 m0, s34
	ds_read_b128 v[186:189], v157 offset:49152
	ds_read_b128 v[190:193], v157 offset:50176
	ds_read_b128 v[194:197], v157 offset:51200
	ds_read_b128 v[198:201], v157 offset:52224
	ds_read_b128 v[202:205], v157 offset:53248
	ds_read_b128 v[206:209], v157 offset:54272
	ds_read_b128 v[210:213], v157 offset:55296
	ds_read_b128 v[214:217], v157 offset:56320
	global_load_lds_dwordx4 v[154:155], off
	s_add_i32 m0, s34, 0x2000
	s_add_u32 s30, s30, 0x80080
	v_lshl_add_u64 v[154:155], v[178:179], 0, s[88:89]
	s_addc_u32 s31, s31, 0
	s_add_i32 s34, s73, s53
	global_load_lds_dwordx4 v[154:155], off
	v_lshl_add_u64 v[154:155], s[30:31], 0, v[140:141]
	s_mov_b32 m0, s34
	s_nop 0
	global_load_lds_dwordx4 v[154:155], off
	v_lshl_add_u64 v[154:155], s[30:31], 0, v[144:145]
	s_add_i32 m0, s34, 0x2000
	s_nop 0
	global_load_lds_dwordx4 v[154:155], off
	v_lshl_add_u64 v[154:155], v[218:219], 0, s[88:89]
	s_mov_b32 m0, s59
	s_nop 0
	global_load_lds_dwordx4 v[154:155], off
	v_lshl_add_u64 v[154:155], v[220:221], 0, s[88:89]
	s_mov_b32 m0, s60
	s_nop 0
	global_load_lds_dwordx4 v[154:155], off
	s_waitcnt vmcnt(8)
	s_waitcnt lgkmcnt(0)
	v_mfma_f32_16x16x32_bf16 v[94:97], v[98:101], v[186:189], v[94:97]
	v_mfma_f32_16x16x32_bf16 v[90:93], v[158:161], v[186:189], v[90:93]
	v_mfma_f32_16x16x32_bf16 v[86:89], v[98:101], v[194:197], v[86:89]
	v_mfma_f32_16x16x32_bf16 v[82:85], v[158:161], v[194:197], v[82:85]
	s_barrier
	s_setprio 1
	v_mfma_f32_16x16x32_bf16 v[78:81], v[98:101], v[202:205], v[78:81]
	v_mfma_f32_16x16x32_bf16 v[74:77], v[158:161], v[202:205], v[74:77]
	v_mfma_f32_16x16x32_bf16 v[70:73], v[98:101], v[210:213], v[70:73]
	v_mfma_f32_16x16x32_bf16 v[66:69], v[158:161], v[210:213], v[66:69]
	v_mfma_f32_16x16x32_bf16 v[94:97], v[102:105], v[190:193], v[94:97]
	v_mfma_f32_16x16x32_bf16 v[90:93], v[162:165], v[190:193], v[90:93]
	v_mfma_f32_16x16x32_bf16 v[86:89], v[102:105], v[198:201], v[86:89]
	v_mfma_f32_16x16x32_bf16 v[82:85], v[162:165], v[198:201], v[82:85]
	v_mfma_f32_16x16x32_bf16 v[78:81], v[102:105], v[206:209], v[78:81]
	v_mfma_f32_16x16x32_bf16 v[74:77], v[162:165], v[206:209], v[74:77]
	v_mfma_f32_16x16x32_bf16 v[70:73], v[102:105], v[214:217], v[70:73]
	v_mfma_f32_16x16x32_bf16 v[66:69], v[162:165], v[214:217], v[66:69]
	v_mfma_f32_16x16x32_bf16 v[30:33], v[166:169], v[186:189], v[30:33]
	v_mfma_f32_16x16x32_bf16 v[26:29], v[174:177], v[186:189], v[26:29]
	v_mfma_f32_16x16x32_bf16 v[22:25], v[166:169], v[194:197], v[22:25]
	v_mfma_f32_16x16x32_bf16 v[18:21], v[174:177], v[194:197], v[18:21]
	v_mfma_f32_16x16x32_bf16 v[14:17], v[166:169], v[202:205], v[14:17]
	v_mfma_f32_16x16x32_bf16 v[10:13], v[174:177], v[202:205], v[10:13]
	v_mfma_f32_16x16x32_bf16 v[6:9], v[166:169], v[210:213], v[6:9]
	v_mfma_f32_16x16x32_bf16 v[2:5], v[174:177], v[210:213], v[2:5]
	v_mfma_f32_16x16x32_bf16 v[30:33], v[170:173], v[190:193], v[30:33]
	v_mfma_f32_16x16x32_bf16 v[26:29], v[182:185], v[190:193], v[26:29]
	v_mfma_f32_16x16x32_bf16 v[22:25], v[170:173], v[198:201], v[22:25]
	v_mfma_f32_16x16x32_bf16 v[18:21], v[182:185], v[198:201], v[18:21]
	v_mfma_f32_16x16x32_bf16 v[14:17], v[170:173], v[206:209], v[14:17]
	v_mfma_f32_16x16x32_bf16 v[10:13], v[182:185], v[206:209], v[10:13]
	v_mfma_f32_16x16x32_bf16 v[6:9], v[170:173], v[214:217], v[6:9]
	v_mfma_f32_16x16x32_bf16 v[2:5], v[182:185], v[214:217], v[2:5]
	s_setprio 0
	s_barrier
	s_add_i32 s70, s70, 2
	s_add_u32 s28, s28, 0x100
	s_addc_u32 s29, s29, 0
	s_add_u32 s66, s66, 0x100
	s_addc_u32 s67, s67, 0
	s_cmp_gt_u32 s70, 29
	s_cbranch_scc0 .LBB0_518
	s_and_b64 vcc, exec, s[16:17]
	s_cbranch_vccz .LBB0_521
	s_barrier

; #define PG8_STAGE(bufoff, gbase, voff) do { _Pragma("unroll") for (int _i = 0; _i < 2; ++_i) \
;         __builtin_amdgcn_global_load_lds((const unsigned*)((const char*)(gbase) + (voff)[_i]), (LAS unsigned*)(lds + (bufoff) + ldsw + _i * 8192), 16, 0, 0); } while (0)
; #define PG8_LDA(dst, b, h) do { _Pragma("unroll") for (int m = 0; m < 4; ++m) _Pragma("unroll") for (int k = 0; k < 2; ++k) dst[m][k] = *(const LAS bf16x8*)(lds + PG8_SA(b, h) + aoff + m * 2048 + k * 1024); } while (0)
; #define PG8_LDB(dst, b, h) do { _Pragma("unroll") for (int n = 0; n < 2; ++n) _Pragma("unroll") for (int k = 0; k < 2; ++k) dst[n][k] = *(const LAS bf16x8*)(lds + PG8_SB(b, h) + boff + n * 2048 + k * 1024); } while (0)
; #define PG8_MMA(ai, bj, At, Bt) do { __builtin_amdgcn_s_setprio(1); _Pragma("unroll") for (int m = 0; m < 4; ++m) _Pragma("unroll") for (int n = 0; n < 2; ++n) _Pragma("unroll") for (int k = 0; k < 2; ++k) \
;         acc[ai][bj][m][n] = __builtin_amdgcn_mfma_f32_16x16x32_bf16(Bt[n][k], At[m][k], acc[ai][bj][m][n], 0, 0, 0); __builtin_amdgcn_s_setprio(0); } while (0)
; #define PG8_WAIT_V(n) asm volatile("s_waitcnt vmcnt(" #n ")" ::: "memory")
; #define PG8_WAIT_L(n) asm volatile("s_waitcnt lgkmcnt(" #n ")" ::: "memory")
; #define PG8_BAR __builtin_amdgcn_s_barrier()
; #define PG8_SCHED __builtin_amdgcn_sched_barrier(0)
; template <class Epi>
; __device__ __forceinline__ void gemm_phase(LAS unsigned char* lds, const Gemm g, const StaticOrder& S, const Epi& E) {
;     ...
;             PG8_LDB(B0, 0, 0); PG8_LDB(B1, 0, 1); PG8_SCHED; PG8_LDA(At, 0, 0); PG8_STAGE(PG8_SA(1, 1), a1 + hA, voffA);
;             PG8_WAIT_V(8); PG8_WAIT_L(0); PG8_BAR; PG8_MMA(0, 0, At, B0); PG8_MMA(0, 1, At, B1); PG8_BAR; PG8_SCHED;
;             PG8_LDA(At, 0, 1); PG8_STAGE(PG8_SB(0, 0), b2, voffB); PG8_STAGE(PG8_SB(0, 1), b2 + hB, voffB); PG8_STAGE(PG8_SA(0, 0), a2, voffA);
;             PG8_WAIT_V(8); PG8_WAIT_L(0); PG8_BAR; PG8_MMA(1, 0, At, B0); PG8_MMA(1, 1, At, B1); PG8_BAR; PG8_SCHED;
.LBB0_1398:
	s_add_u32 s10, s8, 0xfffc0080
	s_addc_u32 s11, s9, -1
	s_add_i32 s35, 0, 0x10000
	s_cmp_eq_u32 s31, 12
	s_cselect_b32 s41, s37, s11
	s_cselect_b32 s40, s36, s10
	s_cselect_b32 s11, s39, s29
	s_cselect_b32 s10, s38, s27
	s_add_i32 s64, 0, 0x14000
	v_add_u32_e32 v158, s35, v180
	v_add_u32_e32 v174, s64, v180
	ds_read_b128 v[146:149], v158
	ds_read_b128 v[150:153], v158 offset:1024
	ds_read_b128 v[154:157], v158 offset:2048
	ds_read_b128 v[158:161], v158 offset:3072
	ds_read_b128 v[162:165], v174
	ds_read_b128 v[166:169], v174 offset:1024
	ds_read_b128 v[170:173], v174 offset:2048
	ds_read_b128 v[174:177], v174 offset:3072
	v_lshl_add_u64 v[178:179], s[8:9], 0, v[142:143]
	s_add_i32 m0, s51, 0xc000
	ds_read_b128 v[182:185], v211
	ds_read_b128 v[186:189], v211 offset:1024
	ds_read_b128 v[190:193], v211 offset:2048
	ds_read_b128 v[194:197], v211 offset:3072
	ds_read_b128 v[198:201], v211 offset:4096
	ds_read_b128 v[202:205], v211 offset:5120
	ds_read_b128 v[216:219], v211 offset:6144
	ds_read_b128 v[232:235], v211 offset:7168
	global_load_lds_dwordx4 v[178:179], off
	v_lshl_add_u64 v[178:179], s[8:9], 0, v[144:145]
	s_add_i32 m0, s51, 0xe000
	s_nop 0
	global_load_lds_dwordx4 v[178:179], off
	s_waitcnt vmcnt(8)
	s_waitcnt lgkmcnt(0)
	v_mfma_f32_16x16x32_bf16 v[126:129], v[146:149], v[182:185], v[126:129]
	v_mfma_f32_16x16x32_bf16 v[122:125], v[154:157], v[182:185], v[122:125]
	v_mfma_f32_16x16x32_bf16 v[110:113], v[146:149], v[190:193], v[110:113]
	v_mfma_f32_16x16x32_bf16 v[106:109], v[154:157], v[190:193], v[106:109]
	s_barrier
	s_setprio 1
	v_mfma_f32_16x16x32_bf16 v[94:97], v[146:149], v[198:201], v[94:97]
	v_mfma_f32_16x16x32_bf16 v[90:93], v[154:157], v[198:201], v[90:93]
	v_mfma_f32_16x16x32_bf16 v[78:81], v[146:149], v[216:219], v[78:81]
	v_mfma_f32_16x16x32_bf16 v[74:77], v[154:157], v[216:219], v[74:77]
	v_mfma_f32_16x16x32_bf16 v[126:129], v[150:153], v[186:189], v[126:129]
	v_mfma_f32_16x16x32_bf16 v[122:125], v[158:161], v[186:189], v[122:125]
	v_mfma_f32_16x16x32_bf16 v[110:113], v[150:153], v[194:197], v[110:113]
	v_mfma_f32_16x16x32_bf16 v[106:109], v[158:161], v[194:197], v[106:109]
	v_mfma_f32_16x16x32_bf16 v[94:97], v[150:153], v[202:205], v[94:97]
	v_mfma_f32_16x16x32_bf16 v[90:93], v[158:161], v[202:205], v[90:93]
	v_mfma_f32_16x16x32_bf16 v[78:81], v[150:153], v[232:235], v[78:81]
	v_mfma_f32_16x16x32_bf16 v[74:77], v[158:161], v[232:235], v[74:77]
	v_mfma_f32_16x16x32_bf16 v[118:121], v[162:165], v[182:185], v[118:121]
	v_mfma_f32_16x16x32_bf16 v[114:117], v[170:173], v[182:185], v[114:117]
	v_mfma_f32_16x16x32_bf16 v[102:105], v[162:165], v[190:193], v[102:105]
	v_mfma_f32_16x16x32_bf16 v[98:101], v[170:173], v[190:193], v[98:101]
	v_mfma_f32_16x16x32_bf16 v[86:89], v[162:165], v[198:201], v[86:89]
	v_mfma_f32_16x16x32_bf16 v[82:85], v[170:173], v[198:201], v[82:85]
	v_mfma_f32_16x16x32_bf16 v[70:73], v[162:165], v[216:219], v[70:73]
	v_mfma_f32_16x16x32_bf16 v[66:69], v[170:173], v[216:219], v[66:69]
	v_mfma_f32_16x16x32_bf16 v[118:121], v[166:169], v[186:189], v[118:121]
	v_mfma_f32_16x16x32_bf16 v[114:117], v[174:177], v[186:189], v[114:117]
	v_mfma_f32_16x16x32_bf16 v[102:105], v[166:169], v[194:197], v[102:105]
	v_mfma_f32_16x16x32_bf16 v[98:101], v[174:177], v[194:197], v[98:101]
	v_mfma_f32_16x16x32_bf16 v[86:89], v[166:169], v[202:205], v[86:89]
	v_mfma_f32_16x16x32_bf16 v[82:85], v[174:177], v[202:205], v[82:85]
	v_mfma_f32_16x16x32_bf16 v[70:73], v[166:169], v[232:235], v[70:73]
	v_mfma_f32_16x16x32_bf16 v[66:69], v[174:177], v[232:235], v[66:69]
	s_setprio 0
	s_barrier
	s_add_i32 s35, s35, s50
	v_lshl_add_u64 v[178:179], s[10:11], 0, v[132:133]
	s_mov_b32 m0, s35
	ds_read_b128 v[182:185], v211 offset:16384
	ds_read_b128 v[186:189], v211 offset:17408
	ds_read_b128 v[190:193], v211 offset:18432
	ds_read_b128 v[194:197], v211 offset:19456
	ds_read_b128 v[198:201], v211 offset:20480
	ds_read_b128 v[202:205], v211 offset:21504
	ds_read_b128 v[216:219], v211 offset:22528
	ds_read_b128 v[232:235], v211 offset:23552
	global_load_lds_dwordx4 v[178:179], off
	s_add_i32 m0, s35, 0x2000
	s_add_u32 s42, s10, 0x40000
	v_lshl_add_u64 v[206:207], s[10:11], 0, v[136:137]
	s_addc_u32 s43, s11, 0
	s_add_i32 s35, s64, s50
	global_load_lds_dwordx4 v[206:207], off
	v_lshl_add_u64 v[220:221], s[42:43], 0, v[132:133]
	s_mov_b32 m0, s35
	v_lshl_add_u64 v[236:237], s[40:41], 0, v[134:135]
	global_load_lds_dwordx4 v[220:221], off
	v_lshl_add_u64 v[220:221], s[42:43], 0, v[136:137]
	s_add_i32 m0, s35, 0x2000
	s_nop 0
	global_load_lds_dwordx4 v[220:221], off
	v_lshl_add_u64 v[220:221], s[40:41], 0, v[130:131]
	s_mov_b32 m0, s51
	s_nop 0
	global_load_lds_dwordx4 v[220:221], off
	s_mov_b32 m0, s52
	s_nop 0
	global_load_lds_dwordx4 v[236:237], off
	s_waitcnt vmcnt(8)
	s_waitcnt lgkmcnt(0)
	v_mfma_f32_16x16x32_bf16 v[62:65], v[146:149], v[182:185], v[62:65]
	v_mfma_f32_16x16x32_bf16 v[58:61], v[154:157], v[182:185], v[58:61]
	v_mfma_f32_16x16x32_bf16 v[46:49], v[146:149], v[190:193], v[46:49]
	v_mfma_f32_16x16x32_bf16 v[42:45], v[154:157], v[190:193], v[42:45]
	s_barrier
; #define PG8_STAGE(bufoff, gbase, voff) do { _Pragma("unroll") for (int _i = 0; _i < 2; ++_i) \
;         __builtin_amdgcn_global_load_lds((const unsigned*)((const char*)(gbase) + (voff)[_i]), (LAS unsigned*)(lds + (bufoff) + ldsw + _i * 8192), 16, 0, 0); } while (0)
; #define PG8_LDA(dst, b, h) do { _Pragma("unroll") for (int m = 0; m < 4; ++m) _Pragma("unroll") for (int k = 0; k < 2; ++k) dst[m][k] = *(const LAS bf16x8*)(lds + PG8_SA(b, h) + aoff + m * 2048 + k * 1024); } while (0)
; #define PG8_LDB(dst, b, h) do { _Pragma("unroll") for (int n = 0; n < 2; ++n) _Pragma("unroll") for (int k = 0; k < 2; ++k) dst[n][k] = *(const LAS bf16x8*)(lds + PG8_SB(b, h) + boff + n * 2048 + k * 1024); } while (0)
; #define PG8_MMA(ai, bj, At, Bt) do { __builtin_amdgcn_s_setprio(1); _Pragma("unroll") for (int m = 0; m < 4; ++m) _Pragma("unroll") for (int n = 0; n < 2; ++n) _Pragma("unroll") for (int k = 0; k < 2; ++k) \
;         acc[ai][bj][m][n] = __builtin_amdgcn_mfma_f32_16x16x32_bf16(Bt[n][k], At[m][k], acc[ai][bj][m][n], 0, 0, 0); __builtin_amdgcn_s_setprio(0); } while (0)
; #define PG8_WAIT_V(n) asm volatile("s_waitcnt vmcnt(" #n ")" ::: "memory")
; #define PG8_WAIT_L(n) asm volatile("s_waitcnt lgkmcnt(" #n ")" ::: "memory")
; #define PG8_BAR __builtin_amdgcn_s_barrier()
; #define PG8_SCHED __builtin_amdgcn_sched_barrier(0)
; template <class Epi>
; __device__ __forceinline__ void gemm_phase(LAS unsigned char* lds, const Gemm g, const StaticOrder& S, const Epi& E) {
;     ...
;             PG8_WAIT_V(8); PG8_WAIT_L(0); PG8_BAR; PG8_MMA(1, 0, At, B0); PG8_MMA(1, 1, At, B1); PG8_BAR; PG8_SCHED;
;             PG8_LDB(B0, 1, 0); PG8_LDB(B1, 1, 1); PG8_SCHED; PG8_LDA(At, 1, 0); PG8_STAGE(PG8_SA(0, 1), a2 + hA, voffA);
;             PG8_WAIT_V(8); PG8_WAIT_L(0); PG8_BAR; PG8_MMA(0, 0, At, B0); PG8_MMA(0, 1, At, B1); PG8_BAR; PG8_SCHED;
	s_setprio 1
	v_mfma_f32_16x16x32_bf16 v[30:33], v[146:149], v[198:201], v[30:33]
	v_mfma_f32_16x16x32_bf16 v[26:29], v[154:157], v[198:201], v[26:29]
	v_mfma_f32_16x16x32_bf16 v[14:17], v[146:149], v[216:219], v[14:17]
	v_mfma_f32_16x16x32_bf16 v[10:13], v[154:157], v[216:219], v[10:13]
	v_mfma_f32_16x16x32_bf16 v[62:65], v[150:153], v[186:189], v[62:65]
	v_mfma_f32_16x16x32_bf16 v[58:61], v[158:161], v[186:189], v[58:61]
	v_mfma_f32_16x16x32_bf16 v[46:49], v[150:153], v[194:197], v[46:49]
	v_mfma_f32_16x16x32_bf16 v[42:45], v[158:161], v[194:197], v[42:45]
	v_mfma_f32_16x16x32_bf16 v[30:33], v[150:153], v[202:205], v[30:33]
	v_mfma_f32_16x16x32_bf16 v[26:29], v[158:161], v[202:205], v[26:29]
	v_mfma_f32_16x16x32_bf16 v[14:17], v[150:153], v[232:235], v[14:17]
	v_mfma_f32_16x16x32_bf16 v[10:13], v[158:161], v[232:235], v[10:13]
	v_mfma_f32_16x16x32_bf16 v[54:57], v[162:165], v[182:185], v[54:57]
	v_mfma_f32_16x16x32_bf16 v[50:53], v[170:173], v[182:185], v[50:53]
	v_mfma_f32_16x16x32_bf16 v[38:41], v[162:165], v[190:193], v[38:41]
	v_mfma_f32_16x16x32_bf16 v[34:37], v[170:173], v[190:193], v[34:37]
	v_mfma_f32_16x16x32_bf16 v[22:25], v[162:165], v[198:201], v[22:25]
	v_mfma_f32_16x16x32_bf16 v[18:21], v[170:173], v[198:201], v[18:21]
	v_mfma_f32_16x16x32_bf16 v[6:9], v[162:165], v[216:219], v[6:9]
	v_mfma_f32_16x16x32_bf16 v[2:5], v[170:173], v[216:219], v[2:5]
	v_mfma_f32_16x16x32_bf16 v[54:57], v[166:169], v[186:189], v[54:57]
	v_mfma_f32_16x16x32_bf16 v[50:53], v[174:177], v[186:189], v[50:53]
	v_mfma_f32_16x16x32_bf16 v[38:41], v[166:169], v[194:197], v[38:41]
	v_mfma_f32_16x16x32_bf16 v[34:37], v[174:177], v[194:197], v[34:37]
	v_mfma_f32_16x16x32_bf16 v[22:25], v[166:169], v[202:205], v[22:25]
	v_mfma_f32_16x16x32_bf16 v[18:21], v[174:177], v[202:205], v[18:21]
	v_mfma_f32_16x16x32_bf16 v[6:9], v[166:169], v[232:235], v[6:9]
	v_mfma_f32_16x16x32_bf16 v[2:5], v[174:177], v[232:235], v[2:5]
	s_setprio 0
	s_barrier
	s_add_i32 s35, 0, 0x18000
	s_add_i32 s42, 0, 0x1c000
	v_add_u32_e32 v158, s35, v180
	v_add_u32_e32 v174, s42, v180
	ds_read_b128 v[146:149], v158
	ds_read_b128 v[150:153], v158 offset:1024
	ds_read_b128 v[154:157], v158 offset:2048
	ds_read_b128 v[158:161], v158 offset:3072
	ds_read_b128 v[162:165], v174
	ds_read_b128 v[166:169], v174 offset:1024
	ds_read_b128 v[170:173], v174 offset:2048
	ds_read_b128 v[174:177], v174 offset:3072
	s_add_u32 s40, s40, 0x40000
	s_addc_u32 s41, s41, 0
	s_mov_b32 m0, s53
	v_lshl_add_u64 v[238:239], s[40:41], 0, v[130:131]
	ds_read_b128 v[182:185], v211 offset:32768
	ds_read_b128 v[186:189], v211 offset:33792
	ds_read_b128 v[190:193], v211 offset:34816
	ds_read_b128 v[194:197], v211 offset:35840
	ds_read_b128 v[198:201], v211 offset:36864
	ds_read_b128 v[202:205], v211 offset:37888
	ds_read_b128 v[216:219], v211 offset:38912
	ds_read_b128 v[232:235], v211 offset:39936
	global_load_lds_dwordx4 v[238:239], off
	v_lshl_add_u64 v[238:239], s[40:41], 0, v[134:135]
	s_mov_b32 m0, s54
	s_nop 0
	global_load_lds_dwordx4 v[238:239], off
	s_waitcnt vmcnt(8)
	s_waitcnt lgkmcnt(0)
	v_mfma_f32_16x16x32_bf16 v[126:129], v[146:149], v[182:185], v[126:129]
	v_mfma_f32_16x16x32_bf16 v[122:125], v[154:157], v[182:185], v[122:125]
	v_mfma_f32_16x16x32_bf16 v[110:113], v[146:149], v[190:193], v[110:113]
	v_mfma_f32_16x16x32_bf16 v[106:109], v[154:157], v[190:193], v[106:109]
	s_barrier
	s_setprio 1
	v_mfma_f32_16x16x32_bf16 v[94:97], v[146:149], v[198:201], v[94:97]
	v_mfma_f32_16x16x32_bf16 v[90:93], v[154:157], v[198:201], v[90:93]
	v_mfma_f32_16x16x32_bf16 v[78:81], v[146:149], v[216:219], v[78:81]
	v_mfma_f32_16x16x32_bf16 v[74:77], v[154:157], v[216:219], v[74:77]
	v_mfma_f32_16x16x32_bf16 v[126:129], v[150:153], v[186:189], v[126:129]
	v_mfma_f32_16x16x32_bf16 v[122:125], v[158:161], v[186:189], v[122:125]
	v_mfma_f32_16x16x32_bf16 v[110:113], v[150:153], v[194:197], v[110:113]
	v_mfma_f32_16x16x32_bf16 v[106:109], v[158:161], v[194:197], v[106:109]
	v_mfma_f32_16x16x32_bf16 v[94:97], v[150:153], v[202:205], v[94:97]
	v_mfma_f32_16x16x32_bf16 v[90:93], v[158:161], v[202:205], v[90:93]
	v_mfma_f32_16x16x32_bf16 v[78:81], v[150:153], v[232:235], v[78:81]
	v_mfma_f32_16x16x32_bf16 v[74:77], v[158:161], v[232:235], v[74:77]
	v_mfma_f32_16x16x32_bf16 v[118:121], v[162:165], v[182:185], v[118:121]
	v_mfma_f32_16x16x32_bf16 v[114:117], v[170:173], v[182:185], v[114:117]
	v_mfma_f32_16x16x32_bf16 v[102:105], v[162:165], v[190:193], v[102:105]
	v_mfma_f32_16x16x32_bf16 v[98:101], v[170:173], v[190:193], v[98:101]
	v_mfma_f32_16x16x32_bf16 v[86:89], v[162:165], v[198:201], v[86:89]
	v_mfma_f32_16x16x32_bf16 v[82:85], v[170:173], v[198:201], v[82:85]
	v_mfma_f32_16x16x32_bf16 v[70:73], v[162:165], v[216:219], v[70:73]
	v_mfma_f32_16x16x32_bf16 v[66:69], v[170:173], v[216:219], v[66:69]
	v_mfma_f32_16x16x32_bf16 v[118:121], v[166:169], v[186:189], v[118:121]
	v_mfma_f32_16x16x32_bf16 v[114:117], v[174:177], v[186:189], v[114:117]
	v_mfma_f32_16x16x32_bf16 v[102:105], v[166:169], v[194:197], v[102:105]
	v_mfma_f32_16x16x32_bf16 v[98:101], v[174:177], v[194:197], v[98:101]
	v_mfma_f32_16x16x32_bf16 v[86:89], v[166:169], v[202:205], v[86:89]
	v_mfma_f32_16x16x32_bf16 v[82:85], v[174:177], v[202:205], v[82:85]
	v_mfma_f32_16x16x32_bf16 v[70:73], v[166:169], v[232:235], v[70:73]
	v_mfma_f32_16x16x32_bf16 v[66:69], v[174:177], v[232:235], v[66:69]
	s_setprio 0
	s_barrier
; #define PG8_STAGE(bufoff, gbase, voff) do { _Pragma("unroll") for (int _i = 0; _i < 2; ++_i) \
;         __builtin_amdgcn_global_load_lds((const unsigned*)((const char*)(gbase) + (voff)[_i]), (LAS unsigned*)(lds + (bufoff) + ldsw + _i * 8192), 16, 0, 0); } while (0)
; #define PG8_LDA(dst, b, h) do { _Pragma("unroll") for (int m = 0; m < 4; ++m) _Pragma("unroll") for (int k = 0; k < 2; ++k) dst[m][k] = *(const LAS bf16x8*)(lds + PG8_SA(b, h) + aoff + m * 2048 + k * 1024); } while (0)
; #define PG8_MMA(ai, bj, At, Bt) do { __builtin_amdgcn_s_setprio(1); _Pragma("unroll") for (int m = 0; m < 4; ++m) _Pragma("unroll") for (int n = 0; n < 2; ++n) _Pragma("unroll") for (int k = 0; k < 2; ++k) \
;         acc[ai][bj][m][n] = __builtin_amdgcn_mfma_f32_16x16x32_bf16(Bt[n][k], At[m][k], acc[ai][bj][m][n], 0, 0, 0); __builtin_amdgcn_s_setprio(0); } while (0)
; #define PG8_WAIT_V(n) asm volatile("s_waitcnt vmcnt(" #n ")" ::: "memory")
; #define PG8_WAIT_L(n) asm volatile("s_waitcnt lgkmcnt(" #n ")" ::: "memory")
; #define PG8_BAR __builtin_amdgcn_s_barrier()
; #define PG8_SCHED __builtin_amdgcn_sched_barrier(0)
; template <class Epi>
; __device__ __forceinline__ void gemm_phase(LAS unsigned char* lds, const Gemm g, const StaticOrder& S, const Epi& E) {
;     ...
;             PG8_LDA(At, 1, 1); PG8_STAGE(PG8_SB(1, 0), b3, voffB); PG8_STAGE(PG8_SB(1, 1), b3 + hB, voffB); PG8_STAGE(PG8_SA(1, 0), a3, voffA);
;             PG8_WAIT_V(8); PG8_WAIT_L(0); PG8_BAR; PG8_MMA(1, 0, At, B0); PG8_MMA(1, 1, At, B1); PG8_BAR; PG8_SCHED;
;         }
;         if (wr == 0) PG8_BAR;
	s_add_i32 s35, s35, s50
	v_lshl_add_u64 v[178:179], v[178:179], 0, s[88:89]
	s_mov_b32 m0, s35
	ds_read_b128 v[182:185], v211 offset:49152
	ds_read_b128 v[186:189], v211 offset:50176
	ds_read_b128 v[190:193], v211 offset:51200
	ds_read_b128 v[194:197], v211 offset:52224
	ds_read_b128 v[198:201], v211 offset:53248
	ds_read_b128 v[202:205], v211 offset:54272
	ds_read_b128 v[216:219], v211 offset:55296
	ds_read_b128 v[232:235], v211 offset:56320
	global_load_lds_dwordx4 v[178:179], off
	s_add_i32 m0, s35, 0x2000
	s_add_u32 s10, s10, 0x40080
	v_lshl_add_u64 v[178:179], v[206:207], 0, s[88:89]
	s_addc_u32 s11, s11, 0
	s_add_i32 s35, s42, s50
	global_load_lds_dwordx4 v[178:179], off
	v_lshl_add_u64 v[178:179], s[10:11], 0, v[132:133]
	s_mov_b32 m0, s35
	s_nop 0
	global_load_lds_dwordx4 v[178:179], off
	v_lshl_add_u64 v[178:179], s[10:11], 0, v[136:137]
	s_add_i32 m0, s35, 0x2000
	s_nop 0
	global_load_lds_dwordx4 v[178:179], off
	v_lshl_add_u64 v[178:179], v[220:221], 0, s[88:89]
	s_mov_b32 m0, s55
	s_nop 0
	global_load_lds_dwordx4 v[178:179], off
	v_lshl_add_u64 v[178:179], v[236:237], 0, s[88:89]
	s_mov_b32 m0, s56
	s_nop 0
	global_load_lds_dwordx4 v[178:179], off
	s_waitcnt vmcnt(8)
	s_waitcnt lgkmcnt(0)
	v_mfma_f32_16x16x32_bf16 v[62:65], v[146:149], v[182:185], v[62:65]
	v_mfma_f32_16x16x32_bf16 v[58:61], v[154:157], v[182:185], v[58:61]
	v_mfma_f32_16x16x32_bf16 v[46:49], v[146:149], v[190:193], v[46:49]
	v_mfma_f32_16x16x32_bf16 v[42:45], v[154:157], v[190:193], v[42:45]
	s_barrier
	s_setprio 1
	v_mfma_f32_16x16x32_bf16 v[30:33], v[146:149], v[198:201], v[30:33]
	v_mfma_f32_16x16x32_bf16 v[26:29], v[154:157], v[198:201], v[26:29]
	v_mfma_f32_16x16x32_bf16 v[14:17], v[146:149], v[216:219], v[14:17]
	v_mfma_f32_16x16x32_bf16 v[10:13], v[154:157], v[216:219], v[10:13]
	v_mfma_f32_16x16x32_bf16 v[62:65], v[150:153], v[186:189], v[62:65]
	v_mfma_f32_16x16x32_bf16 v[58:61], v[158:161], v[186:189], v[58:61]
	v_mfma_f32_16x16x32_bf16 v[46:49], v[150:153], v[194:197], v[46:49]
	v_mfma_f32_16x16x32_bf16 v[42:45], v[158:161], v[194:197], v[42:45]
	v_mfma_f32_16x16x32_bf16 v[30:33], v[150:153], v[202:205], v[30:33]
	v_mfma_f32_16x16x32_bf16 v[26:29], v[158:161], v[202:205], v[26:29]
	v_mfma_f32_16x16x32_bf16 v[14:17], v[150:153], v[232:235], v[14:17]
	v_mfma_f32_16x16x32_bf16 v[10:13], v[158:161], v[232:235], v[10:13]
	v_mfma_f32_16x16x32_bf16 v[54:57], v[162:165], v[182:185], v[54:57]
	v_mfma_f32_16x16x32_bf16 v[50:53], v[170:173], v[182:185], v[50:53]
	v_mfma_f32_16x16x32_bf16 v[38:41], v[162:165], v[190:193], v[38:41]
	v_mfma_f32_16x16x32_bf16 v[34:37], v[170:173], v[190:193], v[34:37]
	v_mfma_f32_16x16x32_bf16 v[22:25], v[162:165], v[198:201], v[22:25]
	v_mfma_f32_16x16x32_bf16 v[18:21], v[170:173], v[198:201], v[18:21]
	v_mfma_f32_16x16x32_bf16 v[6:9], v[162:165], v[216:219], v[6:9]
	v_mfma_f32_16x16x32_bf16 v[2:5], v[170:173], v[216:219], v[2:5]
	v_mfma_f32_16x16x32_bf16 v[54:57], v[166:169], v[186:189], v[54:57]
	v_mfma_f32_16x16x32_bf16 v[50:53], v[174:177], v[186:189], v[50:53]
	v_mfma_f32_16x16x32_bf16 v[38:41], v[166:169], v[194:197], v[38:41]
	v_mfma_f32_16x16x32_bf16 v[34:37], v[174:177], v[194:197], v[34:37]
	v_mfma_f32_16x16x32_bf16 v[22:25], v[166:169], v[202:205], v[22:25]
	v_mfma_f32_16x16x32_bf16 v[18:21], v[174:177], v[202:205], v[18:21]
	v_mfma_f32_16x16x32_bf16 v[6:9], v[166:169], v[232:235], v[6:9]
	v_mfma_f32_16x16x32_bf16 v[2:5], v[174:177], v[232:235], v[2:5]
	s_setprio 0
	s_barrier
	s_add_i32 s31, s31, 2
	s_add_u32 s8, s8, 0x100
	s_addc_u32 s9, s9, 0
	s_add_u32 s27, s27, 0x100
	s_addc_u32 s29, s29, 0
	s_cmp_gt_u32 s31, 13
	s_cbranch_scc0 .LBB0_1398
	s_and_b64 vcc, exec, s[16:17]
	s_cbranch_vccz .LBB0_1401
	s_barrier

; #define PG8_STAGE(bufoff, gbase, voff) do { _Pragma("unroll") for (int _i = 0; _i < 2; ++_i) \
;         __builtin_amdgcn_global_load_lds((const unsigned*)((const char*)(gbase) + (voff)[_i]), (LAS unsigned*)(lds + (bufoff) + ldsw + _i * 8192), 16, 0, 0); } while (0)
; #define PG8_LDA(dst, b, h) do { _Pragma("unroll") for (int m = 0; m < 4; ++m) _Pragma("unroll") for (int k = 0; k < 2; ++k) dst[m][k] = *(const LAS bf16x8*)(lds + PG8_SA(b, h) + aoff + m * 2048 + k * 1024); } while (0)
; #define PG8_LDB(dst, b, h) do { _Pragma("unroll") for (int n = 0; n < 2; ++n) _Pragma("unroll") for (int k = 0; k < 2; ++k) dst[n][k] = *(const LAS bf16x8*)(lds + PG8_SB(b, h) + boff + n * 2048 + k * 1024); } while (0)
; #define PG8_MMA(ai, bj, At, Bt) do { __builtin_amdgcn_s_setprio(1); _Pragma("unroll") for (int m = 0; m < 4; ++m) _Pragma("unroll") for (int n = 0; n < 2; ++n) _Pragma("unroll") for (int k = 0; k < 2; ++k) \
;         acc[ai][bj][m][n] = __builtin_amdgcn_mfma_f32_16x16x32_bf16(Bt[n][k], At[m][k], acc[ai][bj][m][n], 0, 0, 0); __builtin_amdgcn_s_setprio(0); } while (0)
; #define PG8_WAIT_V(n) asm volatile("s_waitcnt vmcnt(" #n ")" ::: "memory")
; #define PG8_WAIT_L(n) asm volatile("s_waitcnt lgkmcnt(" #n ")" ::: "memory")
; #define PG8_BAR __builtin_amdgcn_s_barrier()
; #define PG8_SCHED __builtin_amdgcn_sched_barrier(0)
; template <class Epi>
; __device__ __forceinline__ void gemm_phase(LAS unsigned char* lds, const Gemm g, const StaticOrder& S, const Epi& E) {
;     ...
;             PG8_LDB(B0, 0, 0); PG8_LDB(B1, 0, 1); PG8_SCHED; PG8_LDA(At, 0, 0); PG8_STAGE(PG8_SA(1, 1), a1 + hA, voffA);
;             PG8_WAIT_V(8); PG8_WAIT_L(0); PG8_BAR; PG8_MMA(0, 0, At, B0); PG8_MMA(0, 1, At, B1); PG8_BAR; PG8_SCHED;
;             PG8_LDA(At, 0, 1); PG8_STAGE(PG8_SB(0, 0), b2, voffB); PG8_STAGE(PG8_SB(0, 1), b2 + hB, voffB); PG8_STAGE(PG8_SA(0, 0), a2, voffA);
;             PG8_WAIT_V(8); PG8_WAIT_L(0); PG8_BAR; PG8_MMA(1, 0, At, B0); PG8_MMA(1, 1, At, B1); PG8_BAR; PG8_SCHED;
.LBB0_1550:
	s_add_u32 s22, s20, 0xfffc0080
	s_addc_u32 s23, s21, -1
	s_add_i32 s51, 0, 0x10000
	s_cmp_eq_u32 s50, 12
	s_cselect_b32 s25, s15, s23
	s_cselect_b32 s24, s46, s22
	v_add_u32_e32 v142, s51, v143
	s_cselect_b32 s23, s13, s49
	s_cselect_b32 s22, s47, s48
	s_add_i32 s54, 0, 0x14000
	ds_read_b128 v[148:151], v142
	ds_read_b128 v[152:155], v142 offset:1024
	ds_read_b128 v[156:159], v142 offset:2048
	ds_read_b128 v[160:163], v142 offset:3072
	v_add_u32_e32 v142, s54, v143
	ds_read_b128 v[164:167], v142
	ds_read_b128 v[168:171], v142 offset:1024
	ds_read_b128 v[172:175], v142 offset:2048
	ds_read_b128 v[176:179], v142 offset:3072
	v_lshl_add_u64 v[214:215], s[20:21], 0, v[138:139]
	s_add_i32 m0, s34, 0xc000
	ds_read_b128 v[182:185], v147
	ds_read_b128 v[186:189], v147 offset:1024
	ds_read_b128 v[190:193], v147 offset:2048
	ds_read_b128 v[194:197], v147 offset:3072
	ds_read_b128 v[198:201], v147 offset:4096
	ds_read_b128 v[202:205], v147 offset:5120
	ds_read_b128 v[206:209], v147 offset:6144
	ds_read_b128 v[210:213], v147 offset:7168
	global_load_lds_dwordx4 v[214:215], off
	v_lshl_add_u64 v[214:215], s[20:21], 0, v[140:141]
	s_add_i32 m0, s34, 0xe000
	s_nop 0
	global_load_lds_dwordx4 v[214:215], off
	s_waitcnt vmcnt(8)
	s_waitcnt lgkmcnt(0)
	v_mfma_f32_16x16x32_bf16 v[126:129], v[148:151], v[182:185], v[126:129]
	v_mfma_f32_16x16x32_bf16 v[122:125], v[156:159], v[182:185], v[122:125]
	v_mfma_f32_16x16x32_bf16 v[110:113], v[148:151], v[190:193], v[110:113]
	v_mfma_f32_16x16x32_bf16 v[106:109], v[156:159], v[190:193], v[106:109]
	s_barrier
	s_setprio 1
	v_mfma_f32_16x16x32_bf16 v[94:97], v[148:151], v[198:201], v[94:97]
	v_mfma_f32_16x16x32_bf16 v[90:93], v[156:159], v[198:201], v[90:93]
	v_mfma_f32_16x16x32_bf16 v[78:81], v[148:151], v[206:209], v[78:81]
	v_mfma_f32_16x16x32_bf16 v[74:77], v[156:159], v[206:209], v[74:77]
	v_mfma_f32_16x16x32_bf16 v[126:129], v[152:155], v[186:189], v[126:129]
	v_mfma_f32_16x16x32_bf16 v[122:125], v[160:163], v[186:189], v[122:125]
	v_mfma_f32_16x16x32_bf16 v[110:113], v[152:155], v[194:197], v[110:113]
	v_mfma_f32_16x16x32_bf16 v[106:109], v[160:163], v[194:197], v[106:109]
	v_mfma_f32_16x16x32_bf16 v[94:97], v[152:155], v[202:205], v[94:97]
	v_mfma_f32_16x16x32_bf16 v[90:93], v[160:163], v[202:205], v[90:93]
	v_mfma_f32_16x16x32_bf16 v[78:81], v[152:155], v[210:213], v[78:81]
	v_mfma_f32_16x16x32_bf16 v[74:77], v[160:163], v[210:213], v[74:77]
	v_mfma_f32_16x16x32_bf16 v[118:121], v[164:167], v[182:185], v[118:121]
	v_mfma_f32_16x16x32_bf16 v[114:117], v[172:175], v[182:185], v[114:117]
	v_mfma_f32_16x16x32_bf16 v[102:105], v[164:167], v[190:193], v[102:105]
	v_mfma_f32_16x16x32_bf16 v[98:101], v[172:175], v[190:193], v[98:101]
	v_mfma_f32_16x16x32_bf16 v[86:89], v[164:167], v[198:201], v[86:89]
	v_mfma_f32_16x16x32_bf16 v[82:85], v[172:175], v[198:201], v[82:85]
	v_mfma_f32_16x16x32_bf16 v[70:73], v[164:167], v[206:209], v[70:73]
	v_mfma_f32_16x16x32_bf16 v[66:69], v[172:175], v[206:209], v[66:69]
	v_mfma_f32_16x16x32_bf16 v[118:121], v[168:171], v[186:189], v[118:121]
	v_mfma_f32_16x16x32_bf16 v[114:117], v[176:179], v[186:189], v[114:117]
	v_mfma_f32_16x16x32_bf16 v[102:105], v[168:171], v[194:197], v[102:105]
	v_mfma_f32_16x16x32_bf16 v[98:101], v[176:179], v[194:197], v[98:101]
	v_mfma_f32_16x16x32_bf16 v[86:89], v[168:171], v[202:205], v[86:89]
	v_mfma_f32_16x16x32_bf16 v[82:85], v[176:179], v[202:205], v[82:85]
	v_mfma_f32_16x16x32_bf16 v[70:73], v[168:171], v[210:213], v[70:73]
	v_mfma_f32_16x16x32_bf16 v[66:69], v[176:179], v[210:213], v[66:69]
	s_setprio 0
	s_barrier
	s_add_i32 s51, s51, s31
	v_lshl_add_u64 v[214:215], s[22:23], 0, v[134:135]
	s_mov_b32 m0, s51
	ds_read_b128 v[182:185], v147 offset:16384
	ds_read_b128 v[186:189], v147 offset:17408
	ds_read_b128 v[190:193], v147 offset:18432
	ds_read_b128 v[194:197], v147 offset:19456
	ds_read_b128 v[198:201], v147 offset:20480
	ds_read_b128 v[202:205], v147 offset:21504
	ds_read_b128 v[206:209], v147 offset:22528
	ds_read_b128 v[210:213], v147 offset:23552
	global_load_lds_dwordx4 v[214:215], off
	s_add_i32 m0, s51, 0x2000
	s_add_u32 s52, s22, 0x40000
	v_lshl_add_u64 v[216:217], s[22:23], 0, v[130:131]
	s_addc_u32 s53, s23, 0
	s_add_i32 s51, s54, s31
	global_load_lds_dwordx4 v[216:217], off
	v_lshl_add_u64 v[218:219], s[52:53], 0, v[134:135]
	s_mov_b32 m0, s51
	v_lshl_add_u64 v[220:221], s[24:25], 0, v[132:133]
	global_load_lds_dwordx4 v[218:219], off
	v_lshl_add_u64 v[218:219], s[52:53], 0, v[130:131]
	s_add_i32 m0, s51, 0x2000
	s_nop 0
	global_load_lds_dwordx4 v[218:219], off
	v_lshl_add_u64 v[218:219], s[24:25], 0, v[136:137]
	s_mov_b32 m0, s34
	s_nop 0
	global_load_lds_dwordx4 v[218:219], off
	s_mov_b32 m0, s35
	s_nop 0
	global_load_lds_dwordx4 v[220:221], off
	s_waitcnt vmcnt(8)
	s_waitcnt lgkmcnt(0)
	v_mfma_f32_16x16x32_bf16 v[62:65], v[148:151], v[182:185], v[62:65]
	v_mfma_f32_16x16x32_bf16 v[58:61], v[156:159], v[182:185], v[58:61]
	v_mfma_f32_16x16x32_bf16 v[46:49], v[148:151], v[190:193], v[46:49]
	v_mfma_f32_16x16x32_bf16 v[42:45], v[156:159], v[190:193], v[42:45]
	s_barrier
; #define PG8_STAGE(bufoff, gbase, voff) do { _Pragma("unroll") for (int _i = 0; _i < 2; ++_i) \
;         __builtin_amdgcn_global_load_lds((const unsigned*)((const char*)(gbase) + (voff)[_i]), (LAS unsigned*)(lds + (bufoff) + ldsw + _i * 8192), 16, 0, 0); } while (0)
; #define PG8_LDA(dst, b, h) do { _Pragma("unroll") for (int m = 0; m < 4; ++m) _Pragma("unroll") for (int k = 0; k < 2; ++k) dst[m][k] = *(const LAS bf16x8*)(lds + PG8_SA(b, h) + aoff + m * 2048 + k * 1024); } while (0)
; #define PG8_LDB(dst, b, h) do { _Pragma("unroll") for (int n = 0; n < 2; ++n) _Pragma("unroll") for (int k = 0; k < 2; ++k) dst[n][k] = *(const LAS bf16x8*)(lds + PG8_SB(b, h) + boff + n * 2048 + k * 1024); } while (0)
; #define PG8_MMA(ai, bj, At, Bt) do { __builtin_amdgcn_s_setprio(1); _Pragma("unroll") for (int m = 0; m < 4; ++m) _Pragma("unroll") for (int n = 0; n < 2; ++n) _Pragma("unroll") for (int k = 0; k < 2; ++k) \
;         acc[ai][bj][m][n] = __builtin_amdgcn_mfma_f32_16x16x32_bf16(Bt[n][k], At[m][k], acc[ai][bj][m][n], 0, 0, 0); __builtin_amdgcn_s_setprio(0); } while (0)
; #define PG8_WAIT_V(n) asm volatile("s_waitcnt vmcnt(" #n ")" ::: "memory")
; #define PG8_WAIT_L(n) asm volatile("s_waitcnt lgkmcnt(" #n ")" ::: "memory")
; #define PG8_BAR __builtin_amdgcn_s_barrier()
; #define PG8_SCHED __builtin_amdgcn_sched_barrier(0)
; template <class Epi>
; __device__ __forceinline__ void gemm_phase(LAS unsigned char* lds, const Gemm g, const StaticOrder& S, const Epi& E) {
;     ...
;             PG8_WAIT_V(8); PG8_WAIT_L(0); PG8_BAR; PG8_MMA(1, 0, At, B0); PG8_MMA(1, 1, At, B1); PG8_BAR; PG8_SCHED;
;             PG8_LDB(B0, 1, 0); PG8_LDB(B1, 1, 1); PG8_SCHED; PG8_LDA(At, 1, 0); PG8_STAGE(PG8_SA(0, 1), a2 + hA, voffA);
;             PG8_WAIT_V(8); PG8_WAIT_L(0); PG8_BAR; PG8_MMA(0, 0, At, B0); PG8_MMA(0, 1, At, B1); PG8_BAR; PG8_SCHED;
	s_setprio 1
	v_mfma_f32_16x16x32_bf16 v[30:33], v[148:151], v[198:201], v[30:33]
	v_mfma_f32_16x16x32_bf16 v[26:29], v[156:159], v[198:201], v[26:29]
	v_mfma_f32_16x16x32_bf16 v[14:17], v[148:151], v[206:209], v[14:17]
	v_mfma_f32_16x16x32_bf16 v[10:13], v[156:159], v[206:209], v[10:13]
	v_mfma_f32_16x16x32_bf16 v[62:65], v[152:155], v[186:189], v[62:65]
	v_mfma_f32_16x16x32_bf16 v[58:61], v[160:163], v[186:189], v[58:61]
	v_mfma_f32_16x16x32_bf16 v[46:49], v[152:155], v[194:197], v[46:49]
	v_mfma_f32_16x16x32_bf16 v[42:45], v[160:163], v[194:197], v[42:45]
	v_mfma_f32_16x16x32_bf16 v[30:33], v[152:155], v[202:205], v[30:33]
	v_mfma_f32_16x16x32_bf16 v[26:29], v[160:163], v[202:205], v[26:29]
	v_mfma_f32_16x16x32_bf16 v[14:17], v[152:155], v[210:213], v[14:17]
	v_mfma_f32_16x16x32_bf16 v[10:13], v[160:163], v[210:213], v[10:13]
	v_mfma_f32_16x16x32_bf16 v[54:57], v[164:167], v[182:185], v[54:57]
	v_mfma_f32_16x16x32_bf16 v[50:53], v[172:175], v[182:185], v[50:53]
	v_mfma_f32_16x16x32_bf16 v[38:41], v[164:167], v[190:193], v[38:41]
	v_mfma_f32_16x16x32_bf16 v[34:37], v[172:175], v[190:193], v[34:37]
	v_mfma_f32_16x16x32_bf16 v[22:25], v[164:167], v[198:201], v[22:25]
	v_mfma_f32_16x16x32_bf16 v[18:21], v[172:175], v[198:201], v[18:21]
	v_mfma_f32_16x16x32_bf16 v[6:9], v[164:167], v[206:209], v[6:9]
	v_mfma_f32_16x16x32_bf16 v[2:5], v[172:175], v[206:209], v[2:5]
	v_mfma_f32_16x16x32_bf16 v[54:57], v[168:171], v[186:189], v[54:57]
	v_mfma_f32_16x16x32_bf16 v[50:53], v[176:179], v[186:189], v[50:53]
	v_mfma_f32_16x16x32_bf16 v[38:41], v[168:171], v[194:197], v[38:41]
	v_mfma_f32_16x16x32_bf16 v[34:37], v[176:179], v[194:197], v[34:37]
	v_mfma_f32_16x16x32_bf16 v[22:25], v[168:171], v[202:205], v[22:25]
	v_mfma_f32_16x16x32_bf16 v[18:21], v[176:179], v[202:205], v[18:21]
	v_mfma_f32_16x16x32_bf16 v[6:9], v[168:171], v[210:213], v[6:9]
	v_mfma_f32_16x16x32_bf16 v[2:5], v[176:179], v[210:213], v[2:5]
	s_setprio 0
	s_barrier
	s_add_i32 s51, 0, 0x18000
	v_add_u32_e32 v142, s51, v143
	s_add_i32 s52, 0, 0x1c000
	ds_read_b128 v[148:151], v142
	ds_read_b128 v[152:155], v142 offset:1024
	ds_read_b128 v[156:159], v142 offset:2048
	ds_read_b128 v[160:163], v142 offset:3072
	v_add_u32_e32 v142, s52, v143
	ds_read_b128 v[164:167], v142
	ds_read_b128 v[168:171], v142 offset:1024
	ds_read_b128 v[172:175], v142 offset:2048
	ds_read_b128 v[176:179], v142 offset:3072
	s_add_u32 s24, s24, 0x40000
	s_addc_u32 s25, s25, 0
	s_mov_b32 m0, s36
	v_lshl_add_u64 v[232:233], s[24:25], 0, v[136:137]
	ds_read_b128 v[182:185], v147 offset:32768
	ds_read_b128 v[186:189], v147 offset:33792
	ds_read_b128 v[190:193], v147 offset:34816
	ds_read_b128 v[194:197], v147 offset:35840
	ds_read_b128 v[198:201], v147 offset:36864
	ds_read_b128 v[202:205], v147 offset:37888
	ds_read_b128 v[206:209], v147 offset:38912
	ds_read_b128 v[210:213], v147 offset:39936
	global_load_lds_dwordx4 v[232:233], off
	v_lshl_add_u64 v[232:233], s[24:25], 0, v[132:133]
	s_mov_b32 m0, s37
	s_nop 0
	global_load_lds_dwordx4 v[232:233], off
	s_waitcnt vmcnt(8)
	s_waitcnt lgkmcnt(0)
	v_mfma_f32_16x16x32_bf16 v[126:129], v[148:151], v[182:185], v[126:129]
	v_mfma_f32_16x16x32_bf16 v[122:125], v[156:159], v[182:185], v[122:125]
	v_mfma_f32_16x16x32_bf16 v[110:113], v[148:151], v[190:193], v[110:113]
	v_mfma_f32_16x16x32_bf16 v[106:109], v[156:159], v[190:193], v[106:109]
	s_barrier
	s_setprio 1
	v_mfma_f32_16x16x32_bf16 v[94:97], v[148:151], v[198:201], v[94:97]
	v_mfma_f32_16x16x32_bf16 v[90:93], v[156:159], v[198:201], v[90:93]
	v_mfma_f32_16x16x32_bf16 v[78:81], v[148:151], v[206:209], v[78:81]
	v_mfma_f32_16x16x32_bf16 v[74:77], v[156:159], v[206:209], v[74:77]
	v_mfma_f32_16x16x32_bf16 v[126:129], v[152:155], v[186:189], v[126:129]
	v_mfma_f32_16x16x32_bf16 v[122:125], v[160:163], v[186:189], v[122:125]
	v_mfma_f32_16x16x32_bf16 v[110:113], v[152:155], v[194:197], v[110:113]
	v_mfma_f32_16x16x32_bf16 v[106:109], v[160:163], v[194:197], v[106:109]
	v_mfma_f32_16x16x32_bf16 v[94:97], v[152:155], v[202:205], v[94:97]
	v_mfma_f32_16x16x32_bf16 v[90:93], v[160:163], v[202:205], v[90:93]
	v_mfma_f32_16x16x32_bf16 v[78:81], v[152:155], v[210:213], v[78:81]
	v_mfma_f32_16x16x32_bf16 v[74:77], v[160:163], v[210:213], v[74:77]
	v_mfma_f32_16x16x32_bf16 v[118:121], v[164:167], v[182:185], v[118:121]
	v_mfma_f32_16x16x32_bf16 v[114:117], v[172:175], v[182:185], v[114:117]
	v_mfma_f32_16x16x32_bf16 v[102:105], v[164:167], v[190:193], v[102:105]
	v_mfma_f32_16x16x32_bf16 v[98:101], v[172:175], v[190:193], v[98:101]
	v_mfma_f32_16x16x32_bf16 v[86:89], v[164:167], v[198:201], v[86:89]
	v_mfma_f32_16x16x32_bf16 v[82:85], v[172:175], v[198:201], v[82:85]
	v_mfma_f32_16x16x32_bf16 v[70:73], v[164:167], v[206:209], v[70:73]
	v_mfma_f32_16x16x32_bf16 v[66:69], v[172:175], v[206:209], v[66:69]
	v_mfma_f32_16x16x32_bf16 v[118:121], v[168:171], v[186:189], v[118:121]
	v_mfma_f32_16x16x32_bf16 v[114:117], v[176:179], v[186:189], v[114:117]
	v_mfma_f32_16x16x32_bf16 v[102:105], v[168:171], v[194:197], v[102:105]
	v_mfma_f32_16x16x32_bf16 v[98:101], v[176:179], v[194:197], v[98:101]
	v_mfma_f32_16x16x32_bf16 v[86:89], v[168:171], v[202:205], v[86:89]
	v_mfma_f32_16x16x32_bf16 v[82:85], v[176:179], v[202:205], v[82:85]
	v_mfma_f32_16x16x32_bf16 v[70:73], v[168:171], v[210:213], v[70:73]
	v_mfma_f32_16x16x32_bf16 v[66:69], v[176:179], v[210:213], v[66:69]
	s_setprio 0
	s_barrier
; #define PG8_STAGE(bufoff, gbase, voff) do { _Pragma("unroll") for (int _i = 0; _i < 2; ++_i) \
;         __builtin_amdgcn_global_load_lds((const unsigned*)((const char*)(gbase) + (voff)[_i]), (LAS unsigned*)(lds + (bufoff) + ldsw + _i * 8192), 16, 0, 0); } while (0)
; #define PG8_LDA(dst, b, h) do { _Pragma("unroll") for (int m = 0; m < 4; ++m) _Pragma("unroll") for (int k = 0; k < 2; ++k) dst[m][k] = *(const LAS bf16x8*)(lds + PG8_SA(b, h) + aoff + m * 2048 + k * 1024); } while (0)
; #define PG8_MMA(ai, bj, At, Bt) do { __builtin_amdgcn_s_setprio(1); _Pragma("unroll") for (int m = 0; m < 4; ++m) _Pragma("unroll") for (int n = 0; n < 2; ++n) _Pragma("unroll") for (int k = 0; k < 2; ++k) \
;         acc[ai][bj][m][n] = __builtin_amdgcn_mfma_f32_16x16x32_bf16(Bt[n][k], At[m][k], acc[ai][bj][m][n], 0, 0, 0); __builtin_amdgcn_s_setprio(0); } while (0)
; #define PG8_WAIT_V(n) asm volatile("s_waitcnt vmcnt(" #n ")" ::: "memory")
; #define PG8_WAIT_L(n) asm volatile("s_waitcnt lgkmcnt(" #n ")" ::: "memory")
; #define PG8_BAR __builtin_amdgcn_s_barrier()
; #define PG8_SCHED __builtin_amdgcn_sched_barrier(0)
; template <class Epi>
; __device__ __forceinline__ void gemm_phase(LAS unsigned char* lds, const Gemm g, const StaticOrder& S, const Epi& E) {
;     ...
;             PG8_LDA(At, 1, 1); PG8_STAGE(PG8_SB(1, 0), b3, voffB); PG8_STAGE(PG8_SB(1, 1), b3 + hB, voffB); PG8_STAGE(PG8_SA(1, 0), a3, voffA);
;             PG8_WAIT_V(8); PG8_WAIT_L(0); PG8_BAR; PG8_MMA(1, 0, At, B0); PG8_MMA(1, 1, At, B1); PG8_BAR; PG8_SCHED;
;         }
;         if (wr == 0) PG8_BAR;
	s_add_i32 s24, s51, s31
	v_lshl_add_u64 v[214:215], v[214:215], 0, s[88:89]
	s_mov_b32 m0, s24
	ds_read_b128 v[182:185], v147 offset:49152
	ds_read_b128 v[186:189], v147 offset:50176
	ds_read_b128 v[190:193], v147 offset:51200
	ds_read_b128 v[194:197], v147 offset:52224
	ds_read_b128 v[198:201], v147 offset:53248
	ds_read_b128 v[202:205], v147 offset:54272
	ds_read_b128 v[206:209], v147 offset:55296
	ds_read_b128 v[210:213], v147 offset:56320
	global_load_lds_dwordx4 v[214:215], off
	s_add_i32 m0, s24, 0x2000
	s_add_u32 s22, s22, 0x40080
	v_lshl_add_u64 v[214:215], v[216:217], 0, s[88:89]
	s_addc_u32 s23, s23, 0
	s_add_i32 s24, s52, s31
	global_load_lds_dwordx4 v[214:215], off
	v_lshl_add_u64 v[214:215], s[22:23], 0, v[134:135]
	s_mov_b32 m0, s24
	s_nop 0
	global_load_lds_dwordx4 v[214:215], off
	v_lshl_add_u64 v[214:215], s[22:23], 0, v[130:131]
	s_add_i32 m0, s24, 0x2000
	s_nop 0
	global_load_lds_dwordx4 v[214:215], off
	v_lshl_add_u64 v[214:215], v[218:219], 0, s[88:89]
	s_mov_b32 m0, s38
	s_nop 0
	global_load_lds_dwordx4 v[214:215], off
	v_lshl_add_u64 v[214:215], v[220:221], 0, s[88:89]
	s_mov_b32 m0, s39
	s_nop 0
	global_load_lds_dwordx4 v[214:215], off
	s_waitcnt vmcnt(8)
	s_waitcnt lgkmcnt(0)
	v_mfma_f32_16x16x32_bf16 v[62:65], v[148:151], v[182:185], v[62:65]
	v_mfma_f32_16x16x32_bf16 v[58:61], v[156:159], v[182:185], v[58:61]
	v_mfma_f32_16x16x32_bf16 v[46:49], v[148:151], v[190:193], v[46:49]
	v_mfma_f32_16x16x32_bf16 v[42:45], v[156:159], v[190:193], v[42:45]
	s_barrier
	s_setprio 1
	v_mfma_f32_16x16x32_bf16 v[30:33], v[148:151], v[198:201], v[30:33]
	v_mfma_f32_16x16x32_bf16 v[26:29], v[156:159], v[198:201], v[26:29]
	v_mfma_f32_16x16x32_bf16 v[14:17], v[148:151], v[206:209], v[14:17]
	v_mfma_f32_16x16x32_bf16 v[10:13], v[156:159], v[206:209], v[10:13]
	v_mfma_f32_16x16x32_bf16 v[62:65], v[152:155], v[186:189], v[62:65]
	v_mfma_f32_16x16x32_bf16 v[58:61], v[160:163], v[186:189], v[58:61]
	v_mfma_f32_16x16x32_bf16 v[46:49], v[152:155], v[194:197], v[46:49]
	v_mfma_f32_16x16x32_bf16 v[42:45], v[160:163], v[194:197], v[42:45]
	v_mfma_f32_16x16x32_bf16 v[30:33], v[152:155], v[202:205], v[30:33]
	v_mfma_f32_16x16x32_bf16 v[26:29], v[160:163], v[202:205], v[26:29]
	v_mfma_f32_16x16x32_bf16 v[14:17], v[152:155], v[210:213], v[14:17]
	v_mfma_f32_16x16x32_bf16 v[10:13], v[160:163], v[210:213], v[10:13]
	v_mfma_f32_16x16x32_bf16 v[54:57], v[164:167], v[182:185], v[54:57]
	v_mfma_f32_16x16x32_bf16 v[50:53], v[172:175], v[182:185], v[50:53]
	v_mfma_f32_16x16x32_bf16 v[38:41], v[164:167], v[190:193], v[38:41]
	v_mfma_f32_16x16x32_bf16 v[34:37], v[172:175], v[190:193], v[34:37]
	v_mfma_f32_16x16x32_bf16 v[22:25], v[164:167], v[198:201], v[22:25]
	v_mfma_f32_16x16x32_bf16 v[18:21], v[172:175], v[198:201], v[18:21]
	v_mfma_f32_16x16x32_bf16 v[6:9], v[164:167], v[206:209], v[6:9]
	v_mfma_f32_16x16x32_bf16 v[2:5], v[172:175], v[206:209], v[2:5]
	v_mfma_f32_16x16x32_bf16 v[54:57], v[168:171], v[186:189], v[54:57]
	v_mfma_f32_16x16x32_bf16 v[50:53], v[176:179], v[186:189], v[50:53]
	v_mfma_f32_16x16x32_bf16 v[38:41], v[168:171], v[194:197], v[38:41]
	v_mfma_f32_16x16x32_bf16 v[34:37], v[176:179], v[194:197], v[34:37]
	v_mfma_f32_16x16x32_bf16 v[22:25], v[168:171], v[202:205], v[22:25]
	v_mfma_f32_16x16x32_bf16 v[18:21], v[176:179], v[202:205], v[18:21]
	v_mfma_f32_16x16x32_bf16 v[6:9], v[168:171], v[210:213], v[6:9]
	v_mfma_f32_16x16x32_bf16 v[2:5], v[176:179], v[210:213], v[2:5]
	s_setprio 0
	s_barrier
	s_add_i32 s50, s50, 2
	s_add_u32 s20, s20, 0x100
	s_addc_u32 s21, s21, 0
	s_add_u32 s48, s48, 0x100
	s_addc_u32 s49, s49, 0
	s_cmp_gt_u32 s50, 13
	s_cbranch_scc0 .LBB0_1550
	s_and_b64 vcc, exec, s[10:11]
	s_cbranch_vccz .LBB0_1553
	s_barrier

; #define PG8_STAGE(bufoff, gbase, voff) do { _Pragma("unroll") for (int _i = 0; _i < 2; ++_i) \
;         __builtin_amdgcn_global_load_lds((const unsigned*)((const char*)(gbase) + (voff)[_i]), (LAS unsigned*)(lds + (bufoff) + ldsw + _i * 8192), 16, 0, 0); } while (0)
; #define PG8_LDA(dst, b, h) do { _Pragma("unroll") for (int m = 0; m < 4; ++m) _Pragma("unroll") for (int k = 0; k < 2; ++k) dst[m][k] = *(const LAS bf16x8*)(lds + PG8_SA(b, h) + aoff + m * 2048 + k * 1024); } while (0)
; #define PG8_LDB(dst, b, h) do { _Pragma("unroll") for (int n = 0; n < 2; ++n) _Pragma("unroll") for (int k = 0; k < 2; ++k) dst[n][k] = *(const LAS bf16x8*)(lds + PG8_SB(b, h) + boff + n * 2048 + k * 1024); } while (0)
; #define PG8_MMA(ai, bj, At, Bt) do { __builtin_amdgcn_s_setprio(1); _Pragma("unroll") for (int m = 0; m < 4; ++m) _Pragma("unroll") for (int n = 0; n < 2; ++n) _Pragma("unroll") for (int k = 0; k < 2; ++k) \
;         acc[ai][bj][m][n] = __builtin_amdgcn_mfma_f32_16x16x32_bf16(Bt[n][k], At[m][k], acc[ai][bj][m][n], 0, 0, 0); __builtin_amdgcn_s_setprio(0); } while (0)
; #define PG8_WAIT_V(n) asm volatile("s_waitcnt vmcnt(" #n ")" ::: "memory")
; #define PG8_WAIT_L(n) asm volatile("s_waitcnt lgkmcnt(" #n ")" ::: "memory")
; #define PG8_BAR __builtin_amdgcn_s_barrier()
; #define PG8_SCHED __builtin_amdgcn_sched_barrier(0)
; template <class Epi>
; __device__ __forceinline__ void gemm_phase(LAS unsigned char* lds, const Gemm g, const StaticOrder& S, const Epi& E) {
;     ...
;             PG8_LDB(B0, 0, 0); PG8_LDB(B1, 0, 1); PG8_SCHED; PG8_LDA(At, 0, 0); PG8_STAGE(PG8_SA(1, 1), a1 + hA, voffA);
;             PG8_WAIT_V(8); PG8_WAIT_L(0); PG8_BAR; PG8_MMA(0, 0, At, B0); PG8_MMA(0, 1, At, B1); PG8_BAR; PG8_SCHED;
;             PG8_LDA(At, 0, 1); PG8_STAGE(PG8_SB(0, 0), b2, voffB); PG8_STAGE(PG8_SB(0, 1), b2 + hB, voffB); PG8_STAGE(PG8_SA(0, 0), a2, voffA);
;             PG8_WAIT_V(8); PG8_WAIT_L(0); PG8_BAR; PG8_MMA(1, 0, At, B0); PG8_MMA(1, 1, At, B1); PG8_BAR; PG8_SCHED;
.LBB0_1632:
	s_add_u32 s8, s10, 0x100
	s_addc_u32 s9, s11, 0
	s_add_i32 s70, 0, 0x10000
	s_cmp_eq_u32 s67, 40
	s_cselect_b32 s45, s39, s9
	s_cselect_b32 s44, s38, s8
	s_cselect_b32 s43, s41, s37
	s_cselect_b32 s42, s40, s35
	s_add_i32 s71, 0, 0x14000
	s_waitcnt lgkmcnt(0)
	v_add_u32_e32 v158, s70, v180
	v_add_u32_e32 v174, s71, v180
	ds_read_b128 v[146:149], v158
	ds_read_b128 v[150:153], v158 offset:1024
	ds_read_b128 v[154:157], v158 offset:2048
	ds_read_b128 v[158:161], v158 offset:3072
	ds_read_b128 v[162:165], v174
	ds_read_b128 v[166:169], v174 offset:1024
	ds_read_b128 v[170:173], v174 offset:2048
	ds_read_b128 v[174:177], v174 offset:3072
	v_lshl_add_u64 v[178:179], s[10:11], 0, v[142:143]
	s_add_i32 m0, s52, 0xc000
	ds_read_b128 v[182:185], v192
	ds_read_b128 v[196:199], v192 offset:1024
	ds_read_b128 v[200:203], v192 offset:2048
	ds_read_b128 v[204:207], v192 offset:3072
	ds_read_b128 v[208:211], v192 offset:4096
	ds_read_b128 v[212:215], v192 offset:5120
	ds_read_b128 v[216:219], v192 offset:6144
	ds_read_b128 v[232:235], v192 offset:7168
	global_load_lds_dwordx4 v[178:179], off
	v_lshl_add_u64 v[178:179], s[10:11], 0, v[144:145]
	s_add_i32 m0, s52, 0xe000
	s_nop 0
	global_load_lds_dwordx4 v[178:179], off
	s_waitcnt vmcnt(8)
	s_waitcnt lgkmcnt(0)
	v_mfma_f32_16x16x32_bf16 v[26:29], v[146:149], v[182:185], v[26:29]
	v_mfma_f32_16x16x32_bf16 v[30:33], v[154:157], v[182:185], v[30:33]
	v_mfma_f32_16x16x32_bf16 v[58:61], v[146:149], v[200:203], v[58:61]
	v_mfma_f32_16x16x32_bf16 v[62:65], v[154:157], v[200:203], v[62:65]
	s_barrier
	s_setprio 1
	v_mfma_f32_16x16x32_bf16 v[90:93], v[146:149], v[208:211], v[90:93]
	v_mfma_f32_16x16x32_bf16 v[94:97], v[154:157], v[208:211], v[94:97]
	v_mfma_f32_16x16x32_bf16 v[114:117], v[146:149], v[216:219], v[114:117]
	v_mfma_f32_16x16x32_bf16 v[118:121], v[154:157], v[216:219], v[118:121]
	v_mfma_f32_16x16x32_bf16 v[26:29], v[150:153], v[196:199], v[26:29]
	v_mfma_f32_16x16x32_bf16 v[30:33], v[158:161], v[196:199], v[30:33]
	v_mfma_f32_16x16x32_bf16 v[58:61], v[150:153], v[204:207], v[58:61]
	v_mfma_f32_16x16x32_bf16 v[62:65], v[158:161], v[204:207], v[62:65]
	v_mfma_f32_16x16x32_bf16 v[90:93], v[150:153], v[212:215], v[90:93]
	v_mfma_f32_16x16x32_bf16 v[94:97], v[158:161], v[212:215], v[94:97]
	v_mfma_f32_16x16x32_bf16 v[114:117], v[150:153], v[232:235], v[114:117]
	v_mfma_f32_16x16x32_bf16 v[118:121], v[158:161], v[232:235], v[118:121]
	v_mfma_f32_16x16x32_bf16 v[42:45], v[162:165], v[182:185], v[42:45]
	v_mfma_f32_16x16x32_bf16 v[46:49], v[170:173], v[182:185], v[46:49]
	v_mfma_f32_16x16x32_bf16 v[74:77], v[162:165], v[200:203], v[74:77]
	v_mfma_f32_16x16x32_bf16 v[78:81], v[170:173], v[200:203], v[78:81]
	v_mfma_f32_16x16x32_bf16 v[106:109], v[162:165], v[208:211], v[106:109]
	v_mfma_f32_16x16x32_bf16 v[110:113], v[170:173], v[208:211], v[110:113]
	v_mfma_f32_16x16x32_bf16 v[126:129], v[162:165], v[216:219], v[126:129]
	v_mfma_f32_16x16x32_bf16 v[122:125], v[170:173], v[216:219], v[122:125]
	v_mfma_f32_16x16x32_bf16 v[42:45], v[166:169], v[196:199], v[42:45]
	v_mfma_f32_16x16x32_bf16 v[46:49], v[174:177], v[196:199], v[46:49]
	v_mfma_f32_16x16x32_bf16 v[74:77], v[166:169], v[204:207], v[74:77]
	v_mfma_f32_16x16x32_bf16 v[78:81], v[174:177], v[204:207], v[78:81]
	v_mfma_f32_16x16x32_bf16 v[106:109], v[166:169], v[212:215], v[106:109]
	v_mfma_f32_16x16x32_bf16 v[110:113], v[174:177], v[212:215], v[110:113]
	v_mfma_f32_16x16x32_bf16 v[126:129], v[166:169], v[232:235], v[126:129]
	v_mfma_f32_16x16x32_bf16 v[122:125], v[174:177], v[232:235], v[122:125]
	s_setprio 0
	s_barrier
	s_add_i32 s10, s70, s47
	v_lshl_add_u64 v[178:179], s[42:43], 0, v[132:133]
	s_mov_b32 m0, s10
	ds_read_b128 v[182:185], v192 offset:16384
	ds_read_b128 v[196:199], v192 offset:17408
	ds_read_b128 v[200:203], v192 offset:18432
	ds_read_b128 v[204:207], v192 offset:19456
	ds_read_b128 v[208:211], v192 offset:20480
	ds_read_b128 v[212:215], v192 offset:21504
	ds_read_b128 v[216:219], v192 offset:22528
	ds_read_b128 v[232:235], v192 offset:23552
	global_load_lds_dwordx4 v[178:179], off
	s_add_i32 m0, s10, 0x2000
	s_add_u32 s10, s42, 0xb0000
	v_lshl_add_u64 v[186:187], s[42:43], 0, v[136:137]
	s_addc_u32 s11, s43, 0
	s_add_i32 s70, s71, s47
	global_load_lds_dwordx4 v[186:187], off
	v_lshl_add_u64 v[220:221], s[10:11], 0, v[132:133]
	s_mov_b32 m0, s70
	v_lshl_add_u64 v[236:237], s[44:45], 0, v[134:135]
	global_load_lds_dwordx4 v[220:221], off
	v_lshl_add_u64 v[220:221], s[10:11], 0, v[136:137]
	s_add_i32 m0, s70, 0x2000
	s_nop 0
	global_load_lds_dwordx4 v[220:221], off
	v_lshl_add_u64 v[220:221], s[44:45], 0, v[130:131]
	s_mov_b32 m0, s52
	s_nop 0
	global_load_lds_dwordx4 v[220:221], off
	s_mov_b32 m0, s53
	s_nop 0
	global_load_lds_dwordx4 v[236:237], off
	s_waitcnt vmcnt(8)
	s_waitcnt lgkmcnt(0)
	v_mfma_f32_16x16x32_bf16 v[102:105], v[146:149], v[182:185], v[102:105]
	v_mfma_f32_16x16x32_bf16 v[98:101], v[154:157], v[182:185], v[98:101]
	v_mfma_f32_16x16x32_bf16 v[70:73], v[146:149], v[200:203], v[70:73]
	v_mfma_f32_16x16x32_bf16 v[66:69], v[154:157], v[200:203], v[66:69]
	s_barrier
; #define PG8_STAGE(bufoff, gbase, voff) do { _Pragma("unroll") for (int _i = 0; _i < 2; ++_i) \
;         __builtin_amdgcn_global_load_lds((const unsigned*)((const char*)(gbase) + (voff)[_i]), (LAS unsigned*)(lds + (bufoff) + ldsw + _i * 8192), 16, 0, 0); } while (0)
; #define PG8_LDA(dst, b, h) do { _Pragma("unroll") for (int m = 0; m < 4; ++m) _Pragma("unroll") for (int k = 0; k < 2; ++k) dst[m][k] = *(const LAS bf16x8*)(lds + PG8_SA(b, h) + aoff + m * 2048 + k * 1024); } while (0)
; #define PG8_LDB(dst, b, h) do { _Pragma("unroll") for (int n = 0; n < 2; ++n) _Pragma("unroll") for (int k = 0; k < 2; ++k) dst[n][k] = *(const LAS bf16x8*)(lds + PG8_SB(b, h) + boff + n * 2048 + k * 1024); } while (0)
; #define PG8_MMA(ai, bj, At, Bt) do { __builtin_amdgcn_s_setprio(1); _Pragma("unroll") for (int m = 0; m < 4; ++m) _Pragma("unroll") for (int n = 0; n < 2; ++n) _Pragma("unroll") for (int k = 0; k < 2; ++k) \
;         acc[ai][bj][m][n] = __builtin_amdgcn_mfma_f32_16x16x32_bf16(Bt[n][k], At[m][k], acc[ai][bj][m][n], 0, 0, 0); __builtin_amdgcn_s_setprio(0); } while (0)
; #define PG8_WAIT_V(n) asm volatile("s_waitcnt vmcnt(" #n ")" ::: "memory")
; #define PG8_WAIT_L(n) asm volatile("s_waitcnt lgkmcnt(" #n ")" ::: "memory")
; #define PG8_BAR __builtin_amdgcn_s_barrier()
; #define PG8_SCHED __builtin_amdgcn_sched_barrier(0)
; template <class Epi>
; __device__ __forceinline__ void gemm_phase(LAS unsigned char* lds, const Gemm g, const StaticOrder& S, const Epi& E) {
;     ...
;             PG8_WAIT_V(8); PG8_WAIT_L(0); PG8_BAR; PG8_MMA(1, 0, At, B0); PG8_MMA(1, 1, At, B1); PG8_BAR; PG8_SCHED;
;             PG8_LDB(B0, 1, 0); PG8_LDB(B1, 1, 1); PG8_SCHED; PG8_LDA(At, 1, 0); PG8_STAGE(PG8_SA(0, 1), a2 + hA, voffA);
;             PG8_WAIT_V(8); PG8_WAIT_L(0); PG8_BAR; PG8_MMA(0, 0, At, B0); PG8_MMA(0, 1, At, B1); PG8_BAR; PG8_SCHED;
	s_setprio 1
	v_mfma_f32_16x16x32_bf16 v[38:41], v[146:149], v[208:211], v[38:41]
	v_mfma_f32_16x16x32_bf16 v[34:37], v[154:157], v[208:211], v[34:37]
	v_mfma_f32_16x16x32_bf16 v[14:17], v[146:149], v[216:219], v[14:17]
	v_mfma_f32_16x16x32_bf16 v[10:13], v[154:157], v[216:219], v[10:13]
	v_mfma_f32_16x16x32_bf16 v[102:105], v[150:153], v[196:199], v[102:105]
	v_mfma_f32_16x16x32_bf16 v[98:101], v[158:161], v[196:199], v[98:101]
	v_mfma_f32_16x16x32_bf16 v[70:73], v[150:153], v[204:207], v[70:73]
	v_mfma_f32_16x16x32_bf16 v[66:69], v[158:161], v[204:207], v[66:69]
	v_mfma_f32_16x16x32_bf16 v[38:41], v[150:153], v[212:215], v[38:41]
	v_mfma_f32_16x16x32_bf16 v[34:37], v[158:161], v[212:215], v[34:37]
	v_mfma_f32_16x16x32_bf16 v[14:17], v[150:153], v[232:235], v[14:17]
	v_mfma_f32_16x16x32_bf16 v[10:13], v[158:161], v[232:235], v[10:13]
	v_mfma_f32_16x16x32_bf16 v[86:89], v[162:165], v[182:185], v[86:89]
	v_mfma_f32_16x16x32_bf16 v[82:85], v[170:173], v[182:185], v[82:85]
	v_mfma_f32_16x16x32_bf16 v[54:57], v[162:165], v[200:203], v[54:57]
	v_mfma_f32_16x16x32_bf16 v[50:53], v[170:173], v[200:203], v[50:53]
	v_mfma_f32_16x16x32_bf16 v[22:25], v[162:165], v[208:211], v[22:25]
	v_mfma_f32_16x16x32_bf16 v[18:21], v[170:173], v[208:211], v[18:21]
	v_mfma_f32_16x16x32_bf16 v[6:9], v[162:165], v[216:219], v[6:9]
	v_mfma_f32_16x16x32_bf16 v[2:5], v[170:173], v[216:219], v[2:5]
	v_mfma_f32_16x16x32_bf16 v[86:89], v[166:169], v[196:199], v[86:89]
	v_mfma_f32_16x16x32_bf16 v[82:85], v[174:177], v[196:199], v[82:85]
	v_mfma_f32_16x16x32_bf16 v[54:57], v[166:169], v[204:207], v[54:57]
	v_mfma_f32_16x16x32_bf16 v[50:53], v[174:177], v[204:207], v[50:53]
	v_mfma_f32_16x16x32_bf16 v[22:25], v[166:169], v[212:215], v[22:25]
	v_mfma_f32_16x16x32_bf16 v[18:21], v[174:177], v[212:215], v[18:21]
	v_mfma_f32_16x16x32_bf16 v[6:9], v[166:169], v[232:235], v[6:9]
	v_mfma_f32_16x16x32_bf16 v[2:5], v[174:177], v[232:235], v[2:5]
	s_setprio 0
	s_barrier
	s_add_i32 s70, 0, 0x18000
	s_add_i32 s71, 0, 0x1c000
	v_add_u32_e32 v158, s70, v180
	v_add_u32_e32 v174, s71, v180
	ds_read_b128 v[146:149], v158
	ds_read_b128 v[150:153], v158 offset:1024
	ds_read_b128 v[154:157], v158 offset:2048
	ds_read_b128 v[158:161], v158 offset:3072
	ds_read_b128 v[162:165], v174
	ds_read_b128 v[166:169], v174 offset:1024
	ds_read_b128 v[170:173], v174 offset:2048
	ds_read_b128 v[174:177], v174 offset:3072
	s_add_u32 s10, s44, 0xb0000
	s_addc_u32 s11, s45, 0
	s_mov_b32 m0, s54
	v_lshl_add_u64 v[238:239], s[10:11], 0, v[130:131]
	ds_read_b128 v[182:185], v192 offset:32768
	ds_read_b128 v[196:199], v192 offset:33792
	ds_read_b128 v[200:203], v192 offset:34816
	ds_read_b128 v[204:207], v192 offset:35840
	ds_read_b128 v[208:211], v192 offset:36864
	ds_read_b128 v[212:215], v192 offset:37888
	ds_read_b128 v[216:219], v192 offset:38912
	ds_read_b128 v[232:235], v192 offset:39936
	global_load_lds_dwordx4 v[238:239], off
	v_lshl_add_u64 v[238:239], s[10:11], 0, v[134:135]
	s_mov_b32 m0, s55
	s_nop 0
	global_load_lds_dwordx4 v[238:239], off
	s_waitcnt vmcnt(8)
	s_waitcnt lgkmcnt(0)
	v_mfma_f32_16x16x32_bf16 v[26:29], v[146:149], v[182:185], v[26:29]
	v_mfma_f32_16x16x32_bf16 v[30:33], v[154:157], v[182:185], v[30:33]
	v_mfma_f32_16x16x32_bf16 v[58:61], v[146:149], v[200:203], v[58:61]
	v_mfma_f32_16x16x32_bf16 v[62:65], v[154:157], v[200:203], v[62:65]
	s_barrier
	s_setprio 1
	v_mfma_f32_16x16x32_bf16 v[90:93], v[146:149], v[208:211], v[90:93]
	v_mfma_f32_16x16x32_bf16 v[94:97], v[154:157], v[208:211], v[94:97]
	v_mfma_f32_16x16x32_bf16 v[114:117], v[146:149], v[216:219], v[114:117]
	v_mfma_f32_16x16x32_bf16 v[118:121], v[154:157], v[216:219], v[118:121]
	v_mfma_f32_16x16x32_bf16 v[26:29], v[150:153], v[196:199], v[26:29]
	v_mfma_f32_16x16x32_bf16 v[30:33], v[158:161], v[196:199], v[30:33]
	v_mfma_f32_16x16x32_bf16 v[58:61], v[150:153], v[204:207], v[58:61]
	v_mfma_f32_16x16x32_bf16 v[62:65], v[158:161], v[204:207], v[62:65]
	v_mfma_f32_16x16x32_bf16 v[90:93], v[150:153], v[212:215], v[90:93]
	v_mfma_f32_16x16x32_bf16 v[94:97], v[158:161], v[212:215], v[94:97]
	v_mfma_f32_16x16x32_bf16 v[114:117], v[150:153], v[232:235], v[114:117]
	v_mfma_f32_16x16x32_bf16 v[118:121], v[158:161], v[232:235], v[118:121]
	v_mfma_f32_16x16x32_bf16 v[42:45], v[162:165], v[182:185], v[42:45]
	v_mfma_f32_16x16x32_bf16 v[46:49], v[170:173], v[182:185], v[46:49]
	v_mfma_f32_16x16x32_bf16 v[74:77], v[162:165], v[200:203], v[74:77]
	v_mfma_f32_16x16x32_bf16 v[78:81], v[170:173], v[200:203], v[78:81]
	v_mfma_f32_16x16x32_bf16 v[106:109], v[162:165], v[208:211], v[106:109]
	v_mfma_f32_16x16x32_bf16 v[110:113], v[170:173], v[208:211], v[110:113]
	v_mfma_f32_16x16x32_bf16 v[126:129], v[162:165], v[216:219], v[126:129]
	v_mfma_f32_16x16x32_bf16 v[122:125], v[170:173], v[216:219], v[122:125]
	v_mfma_f32_16x16x32_bf16 v[42:45], v[166:169], v[196:199], v[42:45]
	v_mfma_f32_16x16x32_bf16 v[46:49], v[174:177], v[196:199], v[46:49]
	v_mfma_f32_16x16x32_bf16 v[74:77], v[166:169], v[204:207], v[74:77]
	v_mfma_f32_16x16x32_bf16 v[78:81], v[174:177], v[204:207], v[78:81]
	v_mfma_f32_16x16x32_bf16 v[106:109], v[166:169], v[212:215], v[106:109]
	v_mfma_f32_16x16x32_bf16 v[110:113], v[174:177], v[212:215], v[110:113]
	v_mfma_f32_16x16x32_bf16 v[126:129], v[166:169], v[232:235], v[126:129]
	v_mfma_f32_16x16x32_bf16 v[122:125], v[174:177], v[232:235], v[122:125]
	s_setprio 0
	s_barrier
; #define PG8_STAGE(bufoff, gbase, voff) do { _Pragma("unroll") for (int _i = 0; _i < 2; ++_i) \
;         __builtin_amdgcn_global_load_lds((const unsigned*)((const char*)(gbase) + (voff)[_i]), (LAS unsigned*)(lds + (bufoff) + ldsw + _i * 8192), 16, 0, 0); } while (0)
; #define PG8_LDA(dst, b, h) do { _Pragma("unroll") for (int m = 0; m < 4; ++m) _Pragma("unroll") for (int k = 0; k < 2; ++k) dst[m][k] = *(const LAS bf16x8*)(lds + PG8_SA(b, h) + aoff + m * 2048 + k * 1024); } while (0)
; #define PG8_MMA(ai, bj, At, Bt) do { __builtin_amdgcn_s_setprio(1); _Pragma("unroll") for (int m = 0; m < 4; ++m) _Pragma("unroll") for (int n = 0; n < 2; ++n) _Pragma("unroll") for (int k = 0; k < 2; ++k) \
;         acc[ai][bj][m][n] = __builtin_amdgcn_mfma_f32_16x16x32_bf16(Bt[n][k], At[m][k], acc[ai][bj][m][n], 0, 0, 0); __builtin_amdgcn_s_setprio(0); } while (0)
; #define PG8_WAIT_V(n) asm volatile("s_waitcnt vmcnt(" #n ")" ::: "memory")
; #define PG8_WAIT_L(n) asm volatile("s_waitcnt lgkmcnt(" #n ")" ::: "memory")
; #define PG8_BAR __builtin_amdgcn_s_barrier()
; #define PG8_SCHED __builtin_amdgcn_sched_barrier(0)
; template <class Epi>
; __device__ __forceinline__ void gemm_phase(LAS unsigned char* lds, const Gemm g, const StaticOrder& S, const Epi& E) {
;     ...
;             PG8_LDA(At, 1, 1); PG8_STAGE(PG8_SB(1, 0), b3, voffB); PG8_STAGE(PG8_SB(1, 1), b3 + hB, voffB); PG8_STAGE(PG8_SA(1, 0), a3, voffA);
;             PG8_WAIT_V(8); PG8_WAIT_L(0); PG8_BAR; PG8_MMA(1, 0, At, B0); PG8_MMA(1, 1, At, B1); PG8_BAR; PG8_SCHED;
;         }
;         if (wr == 0) PG8_BAR;
	s_add_i32 s10, s70, s47
	v_lshl_add_u64 v[178:179], v[178:179], 0, s[88:89]
	s_mov_b32 m0, s10
	ds_read_b128 v[182:185], v192 offset:49152
	ds_read_b128 v[196:199], v192 offset:50176
	ds_read_b128 v[200:203], v192 offset:51200
	ds_read_b128 v[204:207], v192 offset:52224
	ds_read_b128 v[208:211], v192 offset:53248
	ds_read_b128 v[212:215], v192 offset:54272
	ds_read_b128 v[216:219], v192 offset:55296
	ds_read_b128 v[232:235], v192 offset:56320
	global_load_lds_dwordx4 v[178:179], off
	s_add_i32 m0, s10, 0x2000
	s_add_u32 s10, s42, 0xb0080
	v_lshl_add_u64 v[178:179], v[186:187], 0, s[88:89]
	s_addc_u32 s11, s43, 0
	s_add_i32 s42, s71, s47
	global_load_lds_dwordx4 v[178:179], off
	v_lshl_add_u64 v[178:179], s[10:11], 0, v[132:133]
	s_mov_b32 m0, s42
	s_nop 0
	global_load_lds_dwordx4 v[178:179], off
	v_lshl_add_u64 v[178:179], s[10:11], 0, v[136:137]
	s_add_i32 m0, s42, 0x2000
	s_nop 0
	global_load_lds_dwordx4 v[178:179], off
	v_lshl_add_u64 v[178:179], v[220:221], 0, s[88:89]
	s_mov_b32 m0, s56
	s_nop 0
	global_load_lds_dwordx4 v[178:179], off
	v_lshl_add_u64 v[178:179], v[236:237], 0, s[88:89]
	s_mov_b32 m0, s57
	s_nop 0
	global_load_lds_dwordx4 v[178:179], off
	s_waitcnt vmcnt(8)
	s_waitcnt lgkmcnt(0)
	v_mfma_f32_16x16x32_bf16 v[102:105], v[146:149], v[182:185], v[102:105]
	v_mfma_f32_16x16x32_bf16 v[98:101], v[154:157], v[182:185], v[98:101]
	v_mfma_f32_16x16x32_bf16 v[70:73], v[146:149], v[200:203], v[70:73]
	v_mfma_f32_16x16x32_bf16 v[66:69], v[154:157], v[200:203], v[66:69]
	s_barrier
	s_setprio 1
	v_mfma_f32_16x16x32_bf16 v[38:41], v[146:149], v[208:211], v[38:41]
	v_mfma_f32_16x16x32_bf16 v[34:37], v[154:157], v[208:211], v[34:37]
	v_mfma_f32_16x16x32_bf16 v[14:17], v[146:149], v[216:219], v[14:17]
	v_mfma_f32_16x16x32_bf16 v[10:13], v[154:157], v[216:219], v[10:13]
	v_mfma_f32_16x16x32_bf16 v[102:105], v[150:153], v[196:199], v[102:105]
	v_mfma_f32_16x16x32_bf16 v[98:101], v[158:161], v[196:199], v[98:101]
	v_mfma_f32_16x16x32_bf16 v[70:73], v[150:153], v[204:207], v[70:73]
	v_mfma_f32_16x16x32_bf16 v[66:69], v[158:161], v[204:207], v[66:69]
	v_mfma_f32_16x16x32_bf16 v[38:41], v[150:153], v[212:215], v[38:41]
	v_mfma_f32_16x16x32_bf16 v[34:37], v[158:161], v[212:215], v[34:37]
	v_mfma_f32_16x16x32_bf16 v[14:17], v[150:153], v[232:235], v[14:17]
	v_mfma_f32_16x16x32_bf16 v[10:13], v[158:161], v[232:235], v[10:13]
	v_mfma_f32_16x16x32_bf16 v[86:89], v[162:165], v[182:185], v[86:89]
	v_mfma_f32_16x16x32_bf16 v[82:85], v[170:173], v[182:185], v[82:85]
	v_mfma_f32_16x16x32_bf16 v[54:57], v[162:165], v[200:203], v[54:57]
	v_mfma_f32_16x16x32_bf16 v[50:53], v[170:173], v[200:203], v[50:53]
	v_mfma_f32_16x16x32_bf16 v[22:25], v[162:165], v[208:211], v[22:25]
	v_mfma_f32_16x16x32_bf16 v[18:21], v[170:173], v[208:211], v[18:21]
	v_mfma_f32_16x16x32_bf16 v[6:9], v[162:165], v[216:219], v[6:9]
	v_mfma_f32_16x16x32_bf16 v[2:5], v[170:173], v[216:219], v[2:5]
	v_mfma_f32_16x16x32_bf16 v[86:89], v[166:169], v[196:199], v[86:89]
	v_mfma_f32_16x16x32_bf16 v[82:85], v[174:177], v[196:199], v[82:85]
	v_mfma_f32_16x16x32_bf16 v[54:57], v[166:169], v[204:207], v[54:57]
	v_mfma_f32_16x16x32_bf16 v[50:53], v[174:177], v[204:207], v[50:53]
	v_mfma_f32_16x16x32_bf16 v[22:25], v[166:169], v[212:215], v[22:25]
	v_mfma_f32_16x16x32_bf16 v[18:21], v[174:177], v[212:215], v[18:21]
	v_mfma_f32_16x16x32_bf16 v[6:9], v[166:169], v[232:235], v[6:9]
	v_mfma_f32_16x16x32_bf16 v[2:5], v[174:177], v[232:235], v[2:5]
	s_setprio 0
	s_barrier
	s_add_i32 s67, s67, 2
	s_add_u32 s35, s35, 0x100
	s_addc_u32 s37, s37, 0
	s_cmp_gt_u32 s67, 41
	s_mov_b64 s[10:11], s[8:9]
	s_cbranch_scc0 .LBB0_1632
	s_and_b64 vcc, exec, s[20:21]
	s_cbranch_vccz .LBB0_1635
	s_barrier
